# route expert-index select: 16-way compare/select chains replaced by packed byte-table v_perm lookups
# speedup vs baseline: 1.0232x; 1.0113x over previous
; __device__ __forceinline__ unsigned ordf(float f) { unsigned u = __float_as_uint(f); return u ^ ((unsigned)((int)u >> 31) | 0x80000000u); }
; __device__ __forceinline__ void route_half(const unsigned char* kp, const bf16* qptr, int r, int hf, unsigned (&L)[16]) {
;     ...
;     for (int blk = 0; blk < 4; ++blk) {
;         f32x16 sc;
; #pragma unroll
;         for (int i = 0; i < 16; ++i) sc[i] = 0.f;
; #pragma unroll
;         for (int ks = 0; ks < 8; ++ks) { const bf16x8 a = *(const bf16x8*)(kp + (blk * 32 + r) * RT_KP + (16 * ks + 8 * hf) * 2);
;             sc = __builtin_amdgcn_mfma_f32_32x32x16_bf16(a, qf[ks], sc, 0, 0, 0); }
;         unsigned kv[16];
; #pragma unroll
;         for (int i = 0; i < 16; ++i) { const unsigned n = (unsigned)(blk * 32 + (i & 3) + 8 * (i >> 2) + 4 * hf); kv[i] = (ordf(sc[i]) & ~0x7Fu) | n; }
.LBB0_134:
	ds_read_b128 v[2:5], v115
	ds_read_b128 v[50:53], v115 offset:32
	v_add_u32_e32 v116, s0, v63
	s_add_i32 s0, s0, 32
	s_cmpk_lg_i32 s0, 0x80
	s_waitcnt vmcnt(7) lgkmcnt(1)
	v_mfma_f32_32x32x16_bf16 v[2:17], v[2:5], v[18:21], 0
	s_waitcnt vmcnt(6) lgkmcnt(0)
	v_mfma_f32_32x32x16_bf16 v[2:17], v[50:53], v[22:25], v[2:17]
	ds_read_b128 v[50:53], v115 offset:64
	s_waitcnt vmcnt(5) lgkmcnt(0)
	v_mfma_f32_32x32x16_bf16 v[2:17], v[50:53], v[26:29], v[2:17]
	ds_read_b128 v[50:53], v115 offset:96
	s_waitcnt vmcnt(4) lgkmcnt(0)
	v_mfma_f32_32x32x16_bf16 v[2:17], v[50:53], v[30:33], v[2:17]
	ds_read_b128 v[50:53], v115 offset:128
	s_waitcnt vmcnt(3) lgkmcnt(0)
	v_mfma_f32_32x32x16_bf16 v[2:17], v[50:53], v[34:37], v[2:17]
	ds_read_b128 v[50:53], v115 offset:160
	s_waitcnt vmcnt(2) lgkmcnt(0)
	v_mfma_f32_32x32x16_bf16 v[2:17], v[50:53], v[38:41], v[2:17]
	ds_read_b128 v[50:53], v115 offset:192
	s_waitcnt vmcnt(1) lgkmcnt(0)
	v_mfma_f32_32x32x16_bf16 v[2:17], v[50:53], v[42:45], v[2:17]
	ds_read_b128 v[50:53], v115 offset:224
	v_add_u32_e32 v115, 0x2200, v115
	s_waitcnt vmcnt(0) lgkmcnt(0)
	v_mfma_f32_32x32x16_bf16 v[2:17], v[50:53], v[46:49], v[2:17]
	s_nop 11
	v_ashrrev_i32_e32 v50, 31, v2
	v_ashrrev_i32_e32 v51, 31, v3
	v_ashrrev_i32_e32 v52, 31, v4
	v_ashrrev_i32_e32 v53, 31, v5
	v_ashrrev_i32_e32 v117, 31, v6
	v_ashrrev_i32_e32 v118, 31, v7
	v_ashrrev_i32_e32 v119, 31, v8
	v_ashrrev_i32_e32 v120, 31, v9
	v_ashrrev_i32_e32 v121, 31, v10
	v_ashrrev_i32_e32 v122, 31, v11
	v_ashrrev_i32_e32 v123, 31, v12
	v_ashrrev_i32_e32 v124, 31, v13
	v_ashrrev_i32_e32 v125, 31, v14
	v_ashrrev_i32_e32 v126, 31, v15
	v_ashrrev_i32_e32 v127, 31, v16
	v_ashrrev_i32_e32 v128, 31, v17
	v_or_b32_e32 v50, 0x80000000, v50
	v_or_b32_e32 v51, 0x80000000, v51
	v_or_b32_e32 v52, 0x80000000, v52
	v_or_b32_e32 v53, 0x80000000, v53
	v_or_b32_e32 v117, 0x80000000, v117
	v_or_b32_e32 v118, 0x80000000, v118
	v_or_b32_e32 v119, 0x80000000, v119
	v_or_b32_e32 v120, 0x80000000, v120
	v_or_b32_e32 v121, 0x80000000, v121
	v_or_b32_e32 v122, 0x80000000, v122
	v_or_b32_e32 v123, 0x80000000, v123
	v_or_b32_e32 v124, 0x80000000, v124
	v_or_b32_e32 v125, 0x80000000, v125
	v_or_b32_e32 v126, 0x80000000, v126
	v_or_b32_e32 v127, 0x80000000, v127
	v_or_b32_e32 v128, 0x80000000, v128
	v_bitop3_b32 v2, v50, s81, v2 bitop3:0x48
	v_bitop3_b32 v3, v51, s81, v3 bitop3:0x48
	v_bitop3_b32 v4, v52, s81, v4 bitop3:0x48
	v_bitop3_b32 v5, v53, s81, v5 bitop3:0x48
	v_bitop3_b32 v6, v117, s81, v6 bitop3:0x48
	v_bitop3_b32 v7, v118, s81, v7 bitop3:0x48
	v_bitop3_b32 v8, v119, s81, v8 bitop3:0x48
	v_bitop3_b32 v9, v120, s81, v9 bitop3:0x48
	v_bitop3_b32 v10, v121, s81, v10 bitop3:0x48
	v_bitop3_b32 v11, v122, s81, v11 bitop3:0x48
	v_bitop3_b32 v12, v123, s81, v12 bitop3:0x48
	v_bitop3_b32 v13, v124, s81, v13 bitop3:0x48
	v_bitop3_b32 v14, v125, s81, v14 bitop3:0x48
	v_bitop3_b32 v15, v126, s81, v15 bitop3:0x48
	v_bitop3_b32 v16, v127, s81, v16 bitop3:0x48
	v_bitop3_b32 v17, v128, s81, v17 bitop3:0x48
	v_add_u32_e32 v2, v116, v2
	v_add3_u32 v3, v116, v3, 1
	v_add3_u32 v4, v116, v4, 2
	v_add3_u32 v5, v116, v5, 3
	v_add3_u32 v6, v116, v6, 8
	v_add3_u32 v7, v116, v7, 9
	v_add3_u32 v8, v116, v8, 10
	v_add3_u32 v9, v116, v9, 11
	v_add3_u32 v10, v116, v10, 16
	v_add3_u32 v11, v116, v11, 17
	v_add3_u32 v12, v116, v12, 18
	v_add3_u32 v13, v116, v13, 19
	v_add3_u32 v14, v116, v14, 24
	v_add3_u32 v15, v116, v15, 25
	v_add3_u32 v16, v116, v16, 26
	v_add3_u32 v17, v116, v17, 27
	v_max_u32_e32 v50, v2, v3
	v_min_u32_e32 v2, v2, v3
	v_max_u32_e32 v3, v5, v4
	v_min_u32_e32 v4, v5, v4
	v_max_u32_e32 v5, v6, v7
	v_min_u32_e32 v6, v6, v7
	v_max_u32_e32 v7, v9, v8
	v_min_u32_e32 v8, v9, v8
	v_max_u32_e32 v9, v10, v11
	v_min_u32_e32 v10, v10, v11
	v_max_u32_e32 v11, v13, v12
	v_min_u32_e32 v12, v13, v12
	v_max_u32_e32 v13, v14, v15
	v_min_u32_e32 v14, v14, v15
	v_max_u32_e32 v15, v17, v16
	v_min_u32_e32 v16, v17, v16
	v_max_u32_e32 v17, v50, v4
	v_min_u32_e32 v4, v50, v4
	v_max_u32_e32 v50, v2, v3
	v_min_u32_e32 v2, v2, v3
	v_max_u32_e32 v3, v8, v5
	v_min_u32_e32 v5, v8, v5
	v_max_u32_e32 v8, v7, v6
	v_min_u32_e32 v6, v7, v6
	v_max_u32_e32 v7, v9, v12
	v_min_u32_e32 v9, v9, v12
	v_max_u32_e32 v12, v10, v11
	v_min_u32_e32 v10, v10, v11
	v_max_u32_e32 v11, v16, v13
	v_min_u32_e32 v13, v16, v13
	v_max_u32_e32 v16, v15, v14
	v_min_u32_e32 v14, v15, v14
	v_max_u32_e32 v15, v17, v50
	v_min_u32_e32 v17, v17, v50
	v_max_u32_e32 v50, v4, v2
	v_min_u32_e32 v2, v4, v2
	v_max_u32_e32 v4, v6, v5
	v_min_u32_e32 v5, v6, v5
	v_max_u32_e32 v6, v8, v3
	v_min_u32_e32 v3, v8, v3
	v_max_u32_e32 v8, v7, v12
	v_min_u32_e32 v7, v7, v12
	v_max_u32_e32 v12, v9, v10
	v_min_u32_e32 v9, v9, v10
	v_max_u32_e32 v10, v14, v13
	v_min_u32_e32 v13, v14, v13
	v_max_u32_e32 v14, v16, v11
	v_min_u32_e32 v11, v16, v11
	v_max_u32_e32 v16, v15, v5
	v_min_u32_e32 v5, v15, v5
	v_max_u32_e32 v15, v17, v4
	v_min_u32_e32 v4, v17, v4
	v_max_u32_e32 v17, v50, v3
	v_min_u32_e32 v3, v50, v3
	v_max_u32_e32 v50, v2, v6
	v_min_u32_e32 v2, v2, v6
	v_max_u32_e32 v6, v13, v8
	v_min_u32_e32 v8, v13, v8
	v_max_u32_e32 v13, v10, v7
	v_min_u32_e32 v7, v10, v7
	v_max_u32_e32 v10, v11, v12
	v_min_u32_e32 v11, v11, v12
	v_max_u32_e32 v12, v14, v9
	v_min_u32_e32 v9, v14, v9
	v_max_u32_e32 v14, v16, v17
	v_min_u32_e32 v16, v16, v17
	v_max_u32_e32 v17, v15, v50
	v_min_u32_e32 v15, v15, v50
	v_max_u32_e32 v50, v5, v3
	v_min_u32_e32 v3, v5, v3
	v_max_u32_e32 v5, v4, v2
	v_min_u32_e32 v2, v4, v2
	v_max_u32_e32 v4, v11, v8
	v_min_u32_e32 v8, v11, v8
	v_max_u32_e32 v11, v9, v7
	v_min_u32_e32 v7, v9, v7
	v_max_u32_e32 v9, v10, v6
	v_min_u32_e32 v6, v10, v6
	v_max_u32_e32 v10, v12, v13
; #define CE_DESC(a, b) do { const unsigned _h = max((a), (b)), _l = min((a), (b)); (a) = _h; (b) = _l; } while (0)
; __device__ __forceinline__ void sort16_desc(unsigned (&v)[16]) {
; #pragma unroll
;     for (int k = 2; k <= 16; k <<= 1)
; #pragma unroll
;         for (int j = k >> 1; j > 0; j >>= 1)
; #pragma unroll
;             for (int i = 0; i < 16; ++i) { const int p = i ^ j; if (p > i) { if ((i & k) == 0) CE_DESC(v[i], v[p]); else CE_DESC(v[p], v[i]); } }
; }
; __device__ __forceinline__ void merge16_desc(unsigned (&a)[16], const unsigned (&b)[16]) {
; #pragma unroll
;     for (int i = 0; i < 16; ++i) a[i] = max(a[i], b[15 - i]);
; #pragma unroll
;     for (int j = 8; j > 0; j >>= 1)
; #pragma unroll
;         for (int i = 0; i < 16; ++i) { const int p = i ^ j; if (p > i) CE_DESC(a[i], a[p]); }
; }
; __device__ __forceinline__ void route_half(const unsigned char* kp, const bf16* qptr, int r, int hf, unsigned (&L)[16]) {
;     ...
;         sort16_desc(kv); merge16_desc(L, kv);
	v_min_u32_e32 v12, v12, v13
	v_max_u32_e32 v13, v14, v17
	v_min_u32_e32 v14, v14, v17
	v_max_u32_e32 v17, v16, v15
	v_min_u32_e32 v15, v16, v15
	v_max_u32_e32 v16, v50, v5
	v_min_u32_e32 v5, v50, v5
	v_max_u32_e32 v50, v3, v2
	v_min_u32_e32 v2, v3, v2
	v_max_u32_e32 v3, v7, v8
	v_min_u32_e32 v7, v7, v8
	v_max_u32_e32 v8, v11, v4
	v_min_u32_e32 v4, v11, v4
	v_max_u32_e32 v11, v12, v6
	v_min_u32_e32 v6, v12, v6
	v_max_u32_e32 v12, v10, v9
	v_min_u32_e32 v9, v10, v9
	v_max_u32_e32 v10, v13, v7
	v_min_u32_e32 v7, v13, v7
	v_max_u32_e32 v13, v14, v3
	v_min_u32_e32 v3, v14, v3
	v_max_u32_e32 v14, v17, v4
	v_min_u32_e32 v4, v17, v4
	v_max_u32_e32 v17, v15, v8
	v_min_u32_e32 v8, v15, v8
	v_max_u32_e32 v15, v16, v6
	v_min_u32_e32 v6, v16, v6
	v_max_u32_e32 v16, v5, v11
	v_min_u32_e32 v5, v5, v11
	v_max_u32_e32 v11, v50, v9
	v_min_u32_e32 v9, v50, v9
	v_max_u32_e32 v50, v2, v12
	v_min_u32_e32 v2, v2, v12
	v_max_u32_e32 v12, v10, v15
	v_min_u32_e32 v10, v10, v15
	v_max_u32_e32 v15, v13, v16
	v_min_u32_e32 v13, v13, v16
	v_max_u32_e32 v16, v14, v11
	v_min_u32_e32 v11, v14, v11
	v_max_u32_e32 v14, v17, v50
	v_min_u32_e32 v17, v17, v50
	v_max_u32_e32 v50, v7, v6
	v_min_u32_e32 v6, v7, v6
	v_max_u32_e32 v7, v3, v5
	v_min_u32_e32 v3, v3, v5
	v_max_u32_e32 v5, v4, v9
	v_min_u32_e32 v4, v4, v9
	v_max_u32_e32 v9, v8, v2
	v_min_u32_e32 v2, v8, v2
	v_max_u32_e32 v8, v12, v16
	v_min_u32_e32 v12, v12, v16
	v_max_u32_e32 v16, v15, v14
	v_min_u32_e32 v14, v15, v14
	v_max_u32_e32 v15, v10, v11
	v_min_u32_e32 v10, v10, v11
	v_max_u32_e32 v11, v13, v17
	v_min_u32_e32 v13, v13, v17
	v_max_u32_e32 v17, v50, v5
	v_min_u32_e32 v5, v50, v5
	v_max_u32_e32 v50, v7, v9
	v_min_u32_e32 v7, v7, v9
	v_max_u32_e32 v9, v6, v4
	v_min_u32_e32 v4, v6, v4
	v_max_u32_e32 v6, v3, v2
	v_min_u32_e32 v2, v3, v2
	v_min_u32_e32 v3, v8, v16
	v_min_u32_e32 v51, v12, v14
	v_min_u32_e32 v52, v15, v11
	v_min_u32_e32 v53, v10, v13
	v_min_u32_e32 v116, v17, v50
	v_min_u32_e32 v117, v5, v7
	v_min_u32_e32 v118, v9, v6
	v_min_u32_e32 v119, v4, v2
	v_max3_u32 v2, v91, v4, v2
	v_max3_u32 v4, v92, v9, v6
	v_max3_u32 v5, v93, v5, v7
	v_max3_u32 v6, v95, v17, v50
	v_max3_u32 v7, v96, v10, v13
	v_max3_u32 v9, v98, v15, v11
	v_max3_u32 v10, v99, v12, v14
	v_max3_u32 v8, v101, v8, v16
	v_max_u32_e32 v11, v83, v119
	v_max_u32_e32 v12, v84, v118
	v_max_u32_e32 v13, v85, v117
	v_max_u32_e32 v14, v86, v116
	v_max_u32_e32 v15, v87, v53
	v_max_u32_e32 v16, v88, v52
	v_max_u32_e32 v17, v89, v51
	v_max_u32_e32 v3, v90, v3
	v_max_u32_e32 v50, v2, v7
	v_min_u32_e32 v2, v2, v7
	v_max_u32_e32 v7, v4, v9
	v_min_u32_e32 v4, v4, v9
	v_max_u32_e32 v9, v5, v10
	v_min_u32_e32 v5, v5, v10
	v_max_u32_e32 v10, v6, v8
	v_min_u32_e32 v6, v6, v8
	v_max_u32_e32 v8, v11, v15
	v_min_u32_e32 v11, v11, v15
	v_max_u32_e32 v15, v12, v16
	v_min_u32_e32 v12, v12, v16
	v_max_u32_e32 v16, v13, v17
	v_min_u32_e32 v13, v13, v17
	v_max_u32_e32 v17, v14, v3
	v_min_u32_e32 v3, v14, v3
	v_max_u32_e32 v14, v50, v9
	v_min_u32_e32 v9, v50, v9
	v_max_u32_e32 v50, v7, v10
	v_min_u32_e32 v7, v7, v10
	v_max_u32_e32 v10, v2, v5
	v_min_u32_e32 v2, v2, v5
	v_max_u32_e32 v5, v4, v6
	v_min_u32_e32 v4, v4, v6
	v_max_u32_e32 v6, v8, v16
	v_min_u32_e32 v8, v8, v16
	v_max_u32_e32 v16, v15, v17
	v_min_u32_e32 v15, v15, v17
	v_max_u32_e32 v17, v11, v13
	v_min_u32_e32 v11, v11, v13
	v_max_u32_e32 v13, v12, v3
	v_min_u32_e32 v3, v12, v3
	v_max_u32_e32 v12, v14, v50
	v_min_u32_e32 v14, v14, v50
	v_max_u32_e32 v50, v9, v7
	v_min_u32_e32 v7, v9, v7
	v_max_u32_e32 v9, v10, v5
	v_min_u32_e32 v5, v10, v5
	v_max_u32_e32 v10, v2, v4
	v_min_u32_e32 v2, v2, v4
	v_max_u32_e32 v4, v6, v16
	v_min_u32_e32 v6, v6, v16
	v_max_u32_e32 v16, v8, v15
	v_min_u32_e32 v8, v8, v15
	v_max_u32_e32 v15, v17, v13
	v_min_u32_e32 v13, v17, v13
	v_max_u32_e32 v17, v11, v3
	v_min_u32_e32 v3, v11, v3
	v_max_u32_e32 v83, v4, v12
	v_min_u32_e32 v91, v4, v12
	v_max_u32_e32 v84, v6, v14
	v_min_u32_e32 v92, v6, v14
	v_max_u32_e32 v85, v16, v50
	v_min_u32_e32 v93, v16, v50
	v_max_u32_e32 v86, v8, v7
	v_min_u32_e32 v95, v8, v7
	v_max_u32_e32 v87, v15, v9
	v_min_u32_e32 v96, v15, v9
	v_max_u32_e32 v88, v13, v5
	v_min_u32_e32 v98, v13, v5
	v_max_u32_e32 v89, v17, v10
	v_min_u32_e32 v99, v17, v10
	v_max_u32_e32 v90, v3, v2
	v_min_u32_e32 v101, v3, v2
	s_cbranch_scc1 .LBB0_134
; __device__ __forceinline__ float unordf(unsigned v) { return __uint_as_float(v ^ ((~(unsigned)((int)v >> 31)) | 0x80000000u)); }
; __device__ __forceinline__ void route_half(const unsigned char* kp, const bf16* qptr, int r, int hf, unsigned (&L)[16]) {
;     ...
;         sort16_desc(kv); merge16_desc(L, kv);
;     }
;     unsigned pk[16];
; #pragma unroll
;     for (int j = 0; j < 16; ++j) pk[j] = (unsigned)__shfl_xor((int)L[j], 32);
;     merge16_desc(L, pk);
; __device__ __forceinline__ void phase_route(CArgs& A, int l, unsigned char* lds, int tid) {
;     ...
;         for (int j = 0; j < 16; ++j) { v1[j] = unordf(L1[j] & ~0x7Fu); v2[j] = unordf(L2[j] & ~0x7Fu); L3[j] = 0u; }
	v_max_u32_e32 v2, v67, v114
	v_max_u32_e32 v3, v68, v113
	v_max_u32_e32 v4, v69, v112
	v_max_u32_e32 v5, v70, v111
	v_max_u32_e32 v6, v71, v110
	v_max_u32_e32 v7, v72, v109
	v_max_u32_e32 v8, v73, v108
	v_max_u32_e32 v9, v74, v107
	v_max_u32_e32 v10, v75, v106
	v_max_u32_e32 v11, v76, v105
	v_max_u32_e32 v12, v77, v104
	v_max_u32_e32 v13, v78, v103
	v_max_u32_e32 v14, v79, v102
	v_max_u32_e32 v15, v80, v100
	v_max_u32_e32 v16, v81, v97
	v_max_u32_e32 v17, v82, v94
	v_max_u32_e32 v18, v2, v10
	v_min_u32_e32 v2, v2, v10
	v_max_u32_e32 v10, v3, v11
	v_min_u32_e32 v3, v3, v11
	v_max_u32_e32 v11, v4, v12
	v_min_u32_e32 v4, v4, v12
	v_max_u32_e32 v12, v5, v13
	v_min_u32_e32 v5, v5, v13
	v_max_u32_e32 v13, v6, v14
	v_min_u32_e32 v6, v6, v14
	v_max_u32_e32 v14, v7, v15
	v_min_u32_e32 v7, v7, v15
	v_max_u32_e32 v15, v8, v16
	v_min_u32_e32 v8, v8, v16
	v_max_u32_e32 v16, v9, v17
	v_min_u32_e32 v9, v9, v17
	v_max_u32_e32 v17, v18, v13
	v_min_u32_e32 v13, v18, v13
	v_max_u32_e32 v18, v10, v14
	v_min_u32_e32 v10, v10, v14
	v_max_u32_e32 v14, v11, v15
	v_min_u32_e32 v11, v11, v15
	v_max_u32_e32 v15, v12, v16
	v_min_u32_e32 v12, v12, v16
	v_max_u32_e32 v16, v2, v6
	v_min_u32_e32 v2, v2, v6
	v_max_u32_e32 v6, v3, v7
	v_min_u32_e32 v3, v3, v7
	v_max_u32_e32 v7, v4, v8
	v_min_u32_e32 v4, v4, v8
	v_max_u32_e32 v8, v5, v9
	v_min_u32_e32 v5, v5, v9
	v_max_u32_e32 v9, v17, v14
	v_min_u32_e32 v14, v17, v14
	v_max_u32_e32 v17, v18, v15
	v_min_u32_e32 v15, v18, v15
	v_max_u32_e32 v18, v13, v11
	v_min_u32_e32 v11, v13, v11
	v_max_u32_e32 v13, v10, v12
	v_min_u32_e32 v10, v10, v12
	v_max_u32_e32 v12, v16, v7
	v_min_u32_e32 v16, v16, v7
	v_max_u32_e32 v19, v6, v8
	v_min_u32_e32 v6, v6, v8
	v_max_u32_e32 v20, v2, v4
	v_min_u32_e32 v2, v2, v4
	v_max_u32_e32 v21, v3, v5
	v_min_u32_e32 v3, v3, v5
	v_max_u32_e32 v4, v9, v17
	v_max_u32_e32 v5, v14, v15
	v_max_u32_e32 v7, v18, v13
	v_max_u32_e32 v8, v11, v10
	v_max_u32_e32 v53, v12, v19
	v_max_u32_e32 v51, v16, v6
	v_max_u32_e32 v49, v20, v21
	v_max_u32_e32 v47, v2, v3
	v_min_u32_e32 v9, v9, v17
	v_min_u32_e32 v69, v14, v15
	v_min_u32_e32 v67, v18, v13
	v_min_u32_e32 v68, v11, v10
	v_min_u32_e32 v52, v12, v19
	v_min_u32_e32 v50, v16, v6
	v_min_u32_e32 v48, v20, v21
	v_min_u32_e32 v46, v2, v3
	ds_bpermute_b32 v2, v64, v83
	ds_bpermute_b32 v3, v64, v91
	ds_bpermute_b32 v6, v64, v84
	ds_bpermute_b32 v10, v64, v92
	ds_bpermute_b32 v11, v64, v85
	ds_bpermute_b32 v12, v64, v93
	ds_bpermute_b32 v13, v64, v86
	ds_bpermute_b32 v14, v64, v95
	ds_bpermute_b32 v15, v64, v87
	ds_bpermute_b32 v16, v64, v96
	ds_bpermute_b32 v17, v64, v88
	ds_bpermute_b32 v18, v64, v101
	ds_bpermute_b32 v19, v64, v90
	ds_bpermute_b32 v20, v64, v99
	ds_bpermute_b32 v21, v64, v89
	ds_bpermute_b32 v22, v64, v98
	s_waitcnt lgkmcnt(4)
	v_max_u32_e32 v18, v83, v18
	s_waitcnt lgkmcnt(3)
	v_max_u32_e32 v19, v91, v19
	s_waitcnt lgkmcnt(2)
	v_max_u32_e32 v20, v84, v20
	s_waitcnt lgkmcnt(1)
	v_max_u32_e32 v21, v92, v21
	s_waitcnt lgkmcnt(0)
	v_max_u32_e32 v22, v85, v22
	v_max_u32_e32 v17, v93, v17
	v_max_u32_e32 v16, v86, v16
	v_max_u32_e32 v15, v95, v15
	v_max_u32_e32 v14, v87, v14
	v_max_u32_e32 v13, v96, v13
	v_max_u32_e32 v12, v88, v12
	v_max_u32_e32 v11, v98, v11
	v_max_u32_e32 v10, v89, v10
	v_max_u32_e32 v6, v99, v6
	v_max_u32_e32 v3, v90, v3
	v_max_u32_e32 v2, v101, v2
	v_max_u32_e32 v23, v18, v14
	v_min_u32_e32 v14, v18, v14
	v_max_u32_e32 v18, v19, v13
	v_min_u32_e32 v13, v19, v13
	v_max_u32_e32 v19, v20, v12
	v_min_u32_e32 v12, v20, v12
	v_max_u32_e32 v20, v21, v11
	v_min_u32_e32 v11, v21, v11
	v_max_u32_e32 v21, v22, v10
	v_min_u32_e32 v10, v22, v10
	v_max_u32_e32 v22, v17, v6
	v_min_u32_e32 v6, v17, v6
	v_max_u32_e32 v17, v16, v3
	v_min_u32_e32 v3, v16, v3
	v_max_u32_e32 v16, v15, v2
	v_min_u32_e32 v2, v15, v2
	v_max_u32_e32 v15, v23, v21
	v_min_u32_e32 v21, v23, v21
	v_max_u32_e32 v23, v18, v22
	v_min_u32_e32 v18, v18, v22
	v_max_u32_e32 v22, v19, v17
	v_min_u32_e32 v17, v19, v17
	v_max_u32_e32 v19, v20, v16
	v_min_u32_e32 v16, v20, v16
	v_max_u32_e32 v20, v14, v10
	v_min_u32_e32 v10, v14, v10
	v_max_u32_e32 v14, v13, v6
	v_min_u32_e32 v6, v13, v6
	v_max_u32_e32 v13, v12, v3
	v_min_u32_e32 v3, v12, v3
	v_max_u32_e32 v12, v11, v2
	v_min_u32_e32 v2, v11, v2
	v_max_u32_e32 v11, v15, v22
	v_min_u32_e32 v15, v15, v22
	v_max_u32_e32 v22, v23, v19
	v_min_u32_e32 v19, v23, v19
	v_max_u32_e32 v23, v21, v17
	v_min_u32_e32 v17, v21, v17
	v_max_u32_e32 v21, v18, v16
	v_min_u32_e32 v16, v18, v16
	v_max_u32_e32 v18, v20, v13
	v_min_u32_e32 v13, v20, v13
	v_max_u32_e32 v20, v14, v12
	v_min_u32_e32 v12, v14, v12
	v_max_u32_e32 v14, v10, v3
	v_min_u32_e32 v3, v10, v3
	v_max_u32_e32 v10, v6, v2
	v_min_u32_e32 v2, v6, v2
	v_cmp_lt_i32_e32 vcc, -1, v4
	v_max_u32_e32 v45, v11, v22
	v_min_u32_e32 v44, v11, v22
	v_max_u32_e32 v11, v3, v2
	v_min_u32_e32 v6, v3, v2
	v_cndmask_b32_e64 v2, v182, -1, vcc
	v_cmp_lt_i32_e32 vcc, -1, v9
	v_max_u32_e32 v35, v13, v12
	v_min_u32_e32 v34, v13, v12
	v_bitop3_b32 v12, v2, v4, s81 bitop3:0x78
	v_cndmask_b32_e64 v2, v182, -1, vcc
	v_cmp_lt_i32_e32 vcc, -1, v44
	v_max_u32_e32 v43, v15, v19
	v_bitop3_b32 v13, v2, v9, s81 bitop3:0x78
	v_cndmask_b32_e64 v2, v182, -1, vcc
	v_cmp_lt_i32_e32 vcc, -1, v5
	v_max_u32_e32 v33, v14, v10
	v_min_u32_e32 v32, v14, v10
	v_bitop3_b32 v14, v2, v44, s81 bitop3:0x78
	v_cndmask_b32_e64 v2, v182, -1, vcc
	v_cmp_lt_i32_e32 vcc, -1, v43
	v_min_u32_e32 v42, v15, v19
	v_bitop3_b32 v15, v2, v5, s81 bitop3:0x78
	v_cndmask_b32_e64 v2, v182, -1, vcc
	v_cmp_lt_i32_e32 vcc, -1, v69
	v_max_u32_e32 v39, v17, v16
	v_min_u32_e32 v38, v17, v16
	v_bitop3_b32 v16, v2, v43, s81 bitop3:0x78
	v_cndmask_b32_e64 v2, v182, -1, vcc
; __device__ __forceinline__ unsigned ordf(float f) { unsigned u = __float_as_uint(f); return u ^ ((unsigned)((int)u >> 31) | 0x80000000u); }
; __device__ __forceinline__ float unordf(unsigned v) { return __uint_as_float(v ^ ((~(unsigned)((int)v >> 31)) | 0x80000000u)); }
; __device__ __forceinline__ void phase_route(CArgs& A, int l, unsigned char* lds, int tid) {
;     ...
;         for (int j = 0; j < 16; ++j) { v1[j] = unordf(L1[j] & ~0x7Fu); v2[j] = unordf(L2[j] & ~0x7Fu); L3[j] = 0u; }
;         {
;             constexpr CandTab CT = make_cand();
;             unsigned g1[16], g2[16];
; #pragma unroll
;             for (int k = 0; k < 16; ++k) {
;                 L3[k] = (ordf(v1[CT.i[k]] + v2[CT.j[k]]) & ~0xFFu) | (unsigned)(CT.i[k] * 16 + CT.j[k]);
;                 g1[k] = (ordf(v1[CT.i[16 + k]] + v2[CT.j[16 + k]]) & ~0xFFu) | (unsigned)(CT.i[16 + k] * 16 + CT.j[16 + k]);
;                 g2[k] = (ordf(v1[CT.i[32 + k]] + v2[CT.j[32 + k]]) & ~0xFFu) | (unsigned)(CT.i[32 + k] * 16 + CT.j[32 + k]); }
	v_cmp_lt_i32_e32 vcc, -1, v42
	v_max_u32_e32 v41, v23, v21
	v_bitop3_b32 v17, v2, v69, s81 bitop3:0x78
	v_cndmask_b32_e64 v2, v182, -1, vcc
	v_cmp_lt_i32_e32 vcc, -1, v7
	v_max_u32_e32 v37, v18, v20
	v_min_u32_e32 v36, v18, v20
	v_bitop3_b32 v18, v2, v42, s81 bitop3:0x78
	v_cndmask_b32_e64 v2, v182, -1, vcc
	v_cmp_lt_i32_e32 vcc, -1, v41
	v_min_u32_e32 v40, v23, v21
	v_bitop3_b32 v19, v2, v7, s81 bitop3:0x78
	v_cndmask_b32_e64 v2, v182, -1, vcc
	v_cmp_lt_i32_e32 vcc, -1, v67
	v_bitop3_b32 v20, v2, v41, s81 bitop3:0x78
	v_and_b32_e32 v78, 0xffffff80, v46
	v_cndmask_b32_e64 v2, v182, -1, vcc
	v_cmp_lt_i32_e32 vcc, -1, v40
	v_bitop3_b32 v21, v2, v67, s81 bitop3:0x78
	s_brev_b32 s0, 1
	v_cndmask_b32_e64 v2, v182, -1, vcc
	v_cmp_lt_i32_e32 vcc, -1, v8
	v_bitop3_b32 v22, v2, v40, s81 bitop3:0x78
	v_and_b32_e32 v40, 0x7f, v40
	v_cndmask_b32_e64 v2, v182, -1, vcc
	v_cmp_lt_i32_e32 vcc, -1, v39
	v_bitop3_b32 v23, v2, v8, s81 bitop3:0x78
	v_and_b32_e32 v41, 0x7f, v41
	v_cndmask_b32_e64 v2, v182, -1, vcc
	v_cmp_lt_i32_e32 vcc, -1, v68
	v_bitop3_b32 v24, v2, v39, s81 bitop3:0x78
	v_and_b32_e32 v39, 0x7f, v39
	v_cndmask_b32_e64 v2, v182, -1, vcc
	v_cmp_lt_i32_e32 vcc, -1, v38
	v_bitop3_b32 v25, v2, v68, s81 bitop3:0x78
	v_and_b32_e32 v42, 0x7f, v42
	v_cndmask_b32_e64 v2, v182, -1, vcc
	v_cmp_lt_i32_e32 vcc, -1, v53
	v_bitop3_b32 v26, v2, v38, s81 bitop3:0x78
	v_and_b32_e32 v38, 0x7f, v38
	v_cndmask_b32_e64 v2, v182, -1, vcc
	v_cmp_lt_i32_e32 vcc, -1, v37
	v_bitop3_b32 v27, v2, v53, s81 bitop3:0x78
	v_and_b32_e32 v43, 0x7f, v43
	v_cndmask_b32_e64 v2, v182, -1, vcc
	v_cmp_lt_i32_e32 vcc, -1, v52
	v_bitop3_b32 v28, v2, v37, s81 bitop3:0x78
	v_and_b32_e32 v37, 0x7f, v37
	v_cndmask_b32_e64 v2, v182, -1, vcc
	v_cmp_lt_i32_e32 vcc, -1, v36
	v_bitop3_b32 v29, v2, v52, s81 bitop3:0x78
	v_and_b32_e32 v44, 0x7f, v44
	v_cndmask_b32_e64 v2, v182, -1, vcc
	v_cmp_lt_i32_e32 vcc, -1, v51
	v_bitop3_b32 v30, v2, v36, s81 bitop3:0x78
	v_add_f32_e32 v30, v12, v30
	v_cndmask_b32_e64 v2, v182, -1, vcc
	v_cmp_lt_i32_e32 vcc, -1, v35
	v_bitop3_b32 v31, v2, v51, s81 bitop3:0x78
	v_and_b32_e32 v36, 0x7f, v36
	v_cndmask_b32_e64 v2, v182, -1, vcc
	v_cmp_lt_i32_e32 vcc, -1, v50
	v_bitop3_b32 v70, v2, v35, s81 bitop3:0x78
	v_add_f32_e32 v70, v12, v70
	v_cndmask_b32_e64 v2, v182, -1, vcc
	v_cmp_lt_i32_e32 vcc, -1, v34
	v_bitop3_b32 v71, v2, v50, s81 bitop3:0x78
	v_and_b32_e32 v35, 0x7f, v35
	v_cndmask_b32_e64 v2, v182, -1, vcc
	v_cmp_lt_i32_e32 vcc, -1, v49
	v_bitop3_b32 v72, v2, v34, s81 bitop3:0x78
	v_add_f32_e32 v72, v12, v72
	v_cndmask_b32_e64 v2, v182, -1, vcc
	v_cmp_lt_i32_e32 vcc, -1, v33
	v_bitop3_b32 v73, v2, v49, s81 bitop3:0x78
	v_and_b32_e32 v34, 0x7f, v34
	v_cndmask_b32_e64 v2, v182, -1, vcc
	v_cmp_lt_i32_e32 vcc, -1, v48
	v_bitop3_b32 v74, v2, v33, s81 bitop3:0x78
	v_add_f32_e32 v74, v12, v74
	v_cndmask_b32_e64 v2, v182, -1, vcc
	v_cmp_lt_i32_e32 vcc, -1, v32
	v_bitop3_b32 v75, v2, v48, s81 bitop3:0x78
	v_and_b32_e32 v33, 0x7f, v33
	v_cndmask_b32_e64 v2, v182, -1, vcc
	v_cmp_lt_i32_e32 vcc, -1, v47
	v_bitop3_b32 v76, v2, v32, s81 bitop3:0x78
	v_and_b32_e32 v32, 0x7f, v32
	v_cndmask_b32_e64 v2, v182, -1, vcc
	v_cmp_lt_i32_e32 vcc, -1, v11
	v_bitop3_b32 v10, v2, v47, s81 bitop3:0x78
	v_and_b32_e32 v47, 0x7f, v47
	v_cndmask_b32_e64 v2, v182, -1, vcc
	v_cmp_lt_i32_e32 vcc, -1, v46
	v_bitop3_b32 v77, v2, v11, s81 bitop3:0x78
	v_and_b32_e32 v2, 0xffffff80, v45
	v_cndmask_b32_e64 v79, v182, -1, vcc
	v_cmp_lt_i32_e32 vcc, -1, v45
	v_add_f32_e32 v77, v12, v77
	v_and_b32_e32 v11, 0x7f, v11
	v_cndmask_b32_e64 v3, v182, -1, vcc
	v_xor_b32_e32 v3, v3, v2
	v_xor_b32_e32 v2, v79, v78
	v_add_f32_e32 v79, v3, v12
	v_ashrrev_i32_e32 v80, 31, v79
	v_or_b32_e32 v80, 0x80000000, v80
	v_bitop3_b32 v79, v80, s82, v79 bitop3:0x48
	v_add_f32_e32 v80, v3, v13
	v_ashrrev_i32_e32 v81, 31, v80
	v_bitop3_b32 v80, v81, v80, s0 bitop3:0x36
	v_add_f32_e32 v81, v17, v18
	v_ashrrev_i32_e32 v82, 31, v81
	v_bitop3_b32 v81, v82, v81, s0 bitop3:0x36
	v_add_f32_e32 v82, v12, v14
	v_ashrrev_i32_e32 v83, 31, v82
	v_bitop3_b32 v82, v83, v82, s0 bitop3:0x36
	v_add_f32_e32 v83, v13, v14
	v_ashrrev_i32_e32 v84, 31, v83
	v_bitop3_b32 v83, v84, v83, s0 bitop3:0x36
	v_add_f32_e32 v84, v3, v19
	v_ashrrev_i32_e32 v85, 31, v84
	v_bitop3_b32 v84, v85, v84, s0 bitop3:0x36
	v_add_f32_e32 v85, v12, v16
	v_ashrrev_i32_e32 v86, 31, v85
	v_bitop3_b32 v85, v86, v85, s0 bitop3:0x36
	v_add_f32_e32 v86, v13, v16
	v_ashrrev_i32_e32 v87, 31, v86
	v_bitop3_b32 v86, v87, v86, s0 bitop3:0x36
	v_add_f32_e32 v87, v19, v14
	v_ashrrev_i32_e32 v88, 31, v87
	v_or_b32_e32 v88, 0x80000000, v88
	v_bitop3_b32 v87, v88, s82, v87 bitop3:0x48
	v_add_f32_e32 v88, v12, v18
	v_ashrrev_i32_e32 v89, 31, v88
	v_bitop3_b32 v88, v89, v88, s0 bitop3:0x36
	v_add_f32_e32 v89, v13, v18
	v_ashrrev_i32_e32 v90, 31, v89
	v_add_f32_e32 v19, v19, v16
	v_bitop3_b32 v89, v90, v89, s0 bitop3:0x36
	v_ashrrev_i32_e32 v90, 31, v19
	v_or_b32_e32 v90, 0x80000000, v90
	v_bitop3_b32 v19, v90, s82, v19 bitop3:0x48
	v_add_f32_e32 v90, v12, v20
	v_ashrrev_i32_e32 v91, 31, v90
	v_bitop3_b32 v90, v91, v90, s0 bitop3:0x36
	v_add_f32_e32 v91, v13, v20
	v_ashrrev_i32_e32 v92, 31, v91
	v_bitop3_b32 v91, v92, v91, s0 bitop3:0x36
	v_add_f32_e32 v92, v3, v21
	v_ashrrev_i32_e32 v93, 31, v92
	v_or_b32_e32 v93, 0x80000000, v93
	v_bitop3_b32 v92, v93, s82, v92 bitop3:0x48
	v_add_f32_e32 v93, v12, v22
	v_ashrrev_i32_e32 v94, 31, v93
	v_add_f32_e32 v22, v13, v22
	v_bitop3_b32 v93, v94, v93, s0 bitop3:0x36
	v_ashrrev_i32_e32 v94, 31, v22
	v_add_f32_e32 v21, v21, v14
	v_bitop3_b32 v22, v94, v22, s0 bitop3:0x36
	v_ashrrev_i32_e32 v94, 31, v21
	v_or_b32_e32 v94, 0x80000000, v94
; __device__ __forceinline__ unsigned ordf(float f) { unsigned u = __float_as_uint(f); return u ^ ((unsigned)((int)u >> 31) | 0x80000000u); }
; __device__ __forceinline__ void phase_route(CArgs& A, int l, unsigned char* lds, int tid) {
;     ...
; #pragma unroll
;             for (int k = 0; k < 16; ++k) {
;                 L3[k] = (ordf(v1[CT.i[k]] + v2[CT.j[k]]) & ~0xFFu) | (unsigned)(CT.i[k] * 16 + CT.j[k]);
;                 g1[k] = (ordf(v1[CT.i[16 + k]] + v2[CT.j[16 + k]]) & ~0xFFu) | (unsigned)(CT.i[16 + k] * 16 + CT.j[16 + k]);
;                 g2[k] = (ordf(v1[CT.i[32 + k]] + v2[CT.j[32 + k]]) & ~0xFFu) | (unsigned)(CT.i[32 + k] * 16 + CT.j[32 + k]); }
;             sort16_desc(L3); sort16_desc(g1); sort16_desc(g2); merge16_desc(L3, g1); merge16_desc(L3, g2);
	v_bitop3_b32 v21, v94, s82, v21 bitop3:0x48
	v_add_f32_e32 v94, v12, v24
	v_ashrrev_i32_e32 v95, 31, v94
	v_add_f32_e32 v24, v13, v24
	v_bitop3_b32 v94, v95, v94, s0 bitop3:0x36
	v_ashrrev_i32_e32 v95, 31, v24
	v_bitop3_b32 v24, v95, v24, s0 bitop3:0x36
	v_add_f32_e32 v95, v3, v23
	v_ashrrev_i32_e32 v96, 31, v95
	v_or_b32_e32 v96, 0x80000000, v96
	v_add_f32_e32 v13, v13, v26
	v_bitop3_b32 v95, v96, s82, v95 bitop3:0x48
	v_add_f32_e32 v96, v12, v26
	v_ashrrev_i32_e32 v26, 31, v13
	v_add_f32_e32 v23, v23, v14
	v_bitop3_b32 v13, v26, v13, s0 bitop3:0x36
	v_ashrrev_i32_e32 v26, 31, v23
	v_or_b32_e32 v26, 0x80000000, v26
	v_bitop3_b32 v23, v26, s82, v23 bitop3:0x48
	v_add_f32_e32 v26, v12, v28
	v_ashrrev_i32_e32 v28, 31, v26
	v_ashrrev_i32_e32 v97, 31, v96
	v_bitop3_b32 v26, v28, v26, s0 bitop3:0x36
	v_add_f32_e32 v28, v3, v15
	v_bitop3_b32 v96, v97, v96, s0 bitop3:0x36
	v_ashrrev_i32_e32 v97, 31, v28
	v_bitop3_b32 v28, v97, v28, s0 bitop3:0x36
	v_add_f32_e32 v97, v3, v25
	v_ashrrev_i32_e32 v98, 31, v97
	v_or_b32_e32 v98, 0x80000000, v98
	v_bitop3_b32 v97, v98, s82, v97 bitop3:0x48
	v_ashrrev_i32_e32 v98, 31, v30
	v_bitop3_b32 v30, v98, v30, s0 bitop3:0x36
	v_add_f32_e32 v98, v15, v14
	v_ashrrev_i32_e32 v99, 31, v98
	v_add_f32_e32 v25, v25, v14
	v_bitop3_b32 v98, v99, v98, s0 bitop3:0x36
	v_ashrrev_i32_e32 v99, 31, v25
	v_or_b32_e32 v99, 0x80000000, v99
	v_bitop3_b32 v25, v99, s82, v25 bitop3:0x48
	v_ashrrev_i32_e32 v99, 31, v70
	v_bitop3_b32 v70, v99, v70, s0 bitop3:0x36
	v_add_f32_e32 v99, v15, v16
	v_ashrrev_i32_e32 v100, 31, v99
	v_add_f32_e32 v27, v3, v27
	v_add_f32_e32 v18, v15, v18
	v_add_f32_e32 v15, v15, v20
	v_bitop3_b32 v99, v100, v99, s0 bitop3:0x36
	v_ashrrev_i32_e32 v100, 31, v27
	v_ashrrev_i32_e32 v20, 31, v15
	v_or_b32_e32 v100, 0x80000000, v100
	v_bitop3_b32 v15, v20, v15, s0 bitop3:0x36
	v_add_f32_e32 v20, v3, v31
	v_bitop3_b32 v27, v100, s82, v27 bitop3:0x48
	v_ashrrev_i32_e32 v100, 31, v72
	v_ashrrev_i32_e32 v31, 31, v20
	v_bitop3_b32 v72, v100, v72, s0 bitop3:0x36
	v_ashrrev_i32_e32 v100, 31, v18
	v_add_f32_e32 v29, v3, v29
	v_or_b32_e32 v31, 0x80000000, v31
	v_bitop3_b32 v18, v100, v18, s0 bitop3:0x36
	v_ashrrev_i32_e32 v100, 31, v29
	v_bitop3_b32 v20, v31, s82, v20 bitop3:0x48
	v_add_f32_e32 v31, v12, v76
	v_or_b32_e32 v100, 0x80000000, v100
	v_ashrrev_i32_e32 v76, 31, v31
	v_bitop3_b32 v29, v100, s82, v29 bitop3:0x48
	v_ashrrev_i32_e32 v100, 31, v74
	v_bitop3_b32 v31, v76, v31, s0 bitop3:0x36
	v_add_f32_e32 v76, v3, v17
	v_cmp_lt_i32_e32 vcc, -1, v6
	v_bitop3_b32 v74, v100, v74, s0 bitop3:0x36
	v_ashrrev_i32_e32 v100, 31, v76
	v_add_f32_e32 v71, v3, v71
	v_cndmask_b32_e64 v78, v182, -1, vcc
	v_bitop3_b32 v76, v100, v76, s0 bitop3:0x36
	v_ashrrev_i32_e32 v100, 31, v71
	v_bitop3_b32 v78, v78, v6, s81 bitop3:0x78
	v_or_b32_e32 v100, 0x80000000, v100
	v_add_f32_e32 v16, v17, v16
	v_bitop3_b32 v71, v100, s82, v71 bitop3:0x48
	v_ashrrev_i32_e32 v100, 31, v77
	v_add_f32_e32 v14, v17, v14
	v_add_f32_e32 v12, v12, v78
	v_ashrrev_i32_e32 v17, 31, v16
	v_bitop3_b32 v77, v100, v77, s0 bitop3:0x36
	v_ashrrev_i32_e32 v100, 31, v14
	v_ashrrev_i32_e32 v78, 31, v12
	v_bitop3_b32 v16, v17, v16, s0 bitop3:0x36
	v_add_f32_e32 v17, v3, v75
	v_bitop3_b32 v14, v100, v14, s0 bitop3:0x36
	v_bitop3_b32 v12, v78, v12, s0 bitop3:0x36
	v_ashrrev_i32_e32 v75, 31, v17
	v_and_or_b32 v80, v80, s82, 16
	v_and_or_b32 v82, v82, s82, 1
	v_and_or_b32 v83, v83, s82, 17
	v_and_or_b32 v85, v85, s82, 2
	v_and_or_b32 v86, v86, s82, 18
	v_and_or_b32 v88, v88, s82, 3
	v_and_or_b32 v89, v89, s82, 19
	v_and_or_b32 v90, v90, s82, 4
	v_and_or_b32 v91, v91, s82, 20
	v_and_or_b32 v93, v93, s82, 5
	v_and_or_b32 v22, v22, s82, 21
	v_and_or_b32 v94, v94, s82, 6
	v_and_or_b32 v24, v24, s82, 22
	v_and_or_b32 v96, v96, s82, 7
	v_and_or_b32 v13, v13, s82, 23
	v_and_or_b32 v26, v26, s82, 8
	v_and_or_b32 v28, v28, s82, 32
	v_and_or_b32 v30, v30, s82, 9
	v_and_or_b32 v98, v98, s82, 33
	v_and_or_b32 v70, v70, s82, 10
	v_and_or_b32 v99, v99, s82, 34
	v_and_or_b32 v72, v72, s82, 11
	v_and_or_b32 v18, v18, s82, 35
	v_and_or_b32 v74, v74, s82, 12
	v_and_or_b32 v15, v15, s82, 36
	v_and_or_b32 v31, v31, s82, 13
	v_and_or_b32 v76, v76, s82, 48
	v_and_or_b32 v77, v77, s82, 14
	v_and_or_b32 v14, v14, s82, 49
	v_and_or_b32 v12, v12, s82, 15
	v_and_or_b32 v16, v16, s82, 50
	v_or_b32_e32 v75, 0x80000000, v75
	v_add_f32_e32 v73, v3, v73
	v_bitop3_b32 v17, v75, s82, v17 bitop3:0x48
	v_max_u32_e32 v75, v79, v82
	v_min_u32_e32 v78, v79, v82
	v_max_u32_e32 v79, v88, v85
	v_min_u32_e32 v82, v88, v85
	v_max_u32_e32 v85, v90, v93
	v_min_u32_e32 v88, v90, v93
	v_max_u32_e32 v90, v96, v94
	v_min_u32_e32 v93, v96, v94
	v_max_u32_e32 v94, v26, v30
	v_min_u32_e32 v26, v26, v30
	v_max_u32_e32 v30, v72, v70
	v_min_u32_e32 v70, v72, v70
	v_max_u32_e32 v72, v74, v31
	v_min_u32_e32 v31, v74, v31
	v_max_u32_e32 v74, v12, v77
	v_min_u32_e32 v12, v12, v77
	v_max_u32_e32 v106, v80, v83
	v_min_u32_e32 v80, v80, v83
	v_max_u32_e32 v83, v89, v86
	v_min_u32_e32 v86, v89, v86
	v_max_u32_e32 v89, v91, v22
	v_min_u32_e32 v22, v91, v22
	v_max_u32_e32 v91, v13, v24
	v_min_u32_e32 v13, v13, v24
	v_max_u32_e32 v24, v28, v98
	v_min_u32_e32 v28, v28, v98
	v_max_u32_e32 v98, v18, v99
	v_min_u32_e32 v18, v18, v99
	v_max_u32_e32 v99, v15, v76
	v_min_u32_e32 v15, v15, v76
	v_max_u32_e32 v76, v16, v14
	v_min_u32_e32 v14, v16, v14
	v_ashrrev_i32_e32 v100, 31, v73
	v_max_u32_e32 v77, v75, v82
	v_min_u32_e32 v75, v75, v82
	v_max_u32_e32 v82, v78, v79
	v_min_u32_e32 v78, v78, v79
	v_max_u32_e32 v79, v93, v85
	v_min_u32_e32 v85, v93, v85
	v_max_u32_e32 v93, v90, v88
	v_min_u32_e32 v88, v90, v88
	v_max_u32_e32 v90, v94, v70
; __device__ __forceinline__ unsigned ordf(float f) { unsigned u = __float_as_uint(f); return u ^ ((unsigned)((int)u >> 31) | 0x80000000u); }
; #define CE_DESC(a, b) do { const unsigned _h = max((a), (b)), _l = min((a), (b)); (a) = _h; (b) = _l; } while (0)
; __device__ __forceinline__ void sort16_desc(unsigned (&v)[16]) {
; #pragma unroll
;     for (int k = 2; k <= 16; k <<= 1)
; #pragma unroll
;         for (int j = k >> 1; j > 0; j >>= 1)
; #pragma unroll
;             for (int i = 0; i < 16; ++i) { const int p = i ^ j; if (p > i) { if ((i & k) == 0) CE_DESC(v[i], v[p]); else CE_DESC(v[p], v[i]); } }
; }
; __device__ __forceinline__ void phase_route(CArgs& A, int l, unsigned char* lds, int tid) {
;     ...
;                 L3[k] = (ordf(v1[CT.i[k]] + v2[CT.j[k]]) & ~0xFFu) | (unsigned)(CT.i[k] * 16 + CT.j[k]);
;                 g1[k] = (ordf(v1[CT.i[16 + k]] + v2[CT.j[16 + k]]) & ~0xFFu) | (unsigned)(CT.i[16 + k] * 16 + CT.j[16 + k]);
;                 g2[k] = (ordf(v1[CT.i[32 + k]] + v2[CT.j[32 + k]]) & ~0xFFu) | (unsigned)(CT.i[32 + k] * 16 + CT.j[32 + k]); }
;             sort16_desc(L3); sort16_desc(g1); sort16_desc(g2); merge16_desc(L3, g1); merge16_desc(L3, g2);
	v_min_u32_e32 v70, v94, v70
	v_max_u32_e32 v94, v26, v30
	v_min_u32_e32 v26, v26, v30
	v_max_u32_e32 v30, v12, v72
	v_min_u32_e32 v12, v12, v72
	v_max_u32_e32 v72, v74, v31
	v_min_u32_e32 v31, v74, v31
	v_max_u32_e32 v16, v106, v86
	v_min_u32_e32 v86, v106, v86
	v_max_u32_e32 v106, v80, v83
	v_min_u32_e32 v80, v80, v83
	v_max_u32_e32 v83, v13, v89
	v_min_u32_e32 v13, v13, v89
	v_max_u32_e32 v89, v91, v22
	v_min_u32_e32 v22, v91, v22
	v_max_u32_e32 v91, v24, v18
	v_min_u32_e32 v18, v24, v18
	v_max_u32_e32 v24, v28, v98
	v_min_u32_e32 v28, v28, v98
	v_max_u32_e32 v98, v14, v99
	v_min_u32_e32 v14, v14, v99
	v_max_u32_e32 v99, v76, v15
	v_min_u32_e32 v15, v76, v15
	v_or_b32_e32 v100, 0x80000000, v100
	v_max_u32_e32 v74, v77, v82
	v_min_u32_e32 v77, v77, v82
	v_max_u32_e32 v82, v75, v78
	v_min_u32_e32 v75, v75, v78
	v_max_u32_e32 v78, v88, v85
	v_min_u32_e32 v85, v88, v85
	v_max_u32_e32 v88, v93, v79
	v_min_u32_e32 v79, v93, v79
	v_max_u32_e32 v93, v90, v94
	v_min_u32_e32 v90, v90, v94
	v_max_u32_e32 v94, v70, v26
	v_min_u32_e32 v26, v70, v26
	v_max_u32_e32 v70, v31, v12
	v_min_u32_e32 v12, v31, v12
	v_max_u32_e32 v31, v72, v30
	v_min_u32_e32 v30, v72, v30
	v_max_u32_e32 v76, v16, v106
	v_min_u32_e32 v16, v16, v106
	v_max_u32_e32 v106, v86, v80
	v_min_u32_e32 v80, v86, v80
	v_max_u32_e32 v86, v22, v13
	v_min_u32_e32 v13, v22, v13
	v_max_u32_e32 v22, v89, v83
	v_min_u32_e32 v83, v89, v83
	v_max_u32_e32 v89, v91, v24
	v_min_u32_e32 v24, v91, v24
	v_max_u32_e32 v91, v18, v28
	v_min_u32_e32 v18, v18, v28
	v_max_u32_e32 v28, v15, v14
	v_min_u32_e32 v14, v15, v14
	v_max_u32_e32 v15, v99, v98
	v_min_u32_e32 v98, v99, v98
	v_bitop3_b32 v73, v100, s82, v73 bitop3:0x48
	v_max_u32_e32 v72, v74, v85
	v_min_u32_e32 v74, v74, v85
	v_max_u32_e32 v85, v77, v78
	v_min_u32_e32 v77, v77, v78
	v_max_u32_e32 v78, v82, v79
	v_min_u32_e32 v79, v82, v79
	v_max_u32_e32 v82, v75, v88
	v_min_u32_e32 v75, v75, v88
	v_max_u32_e32 v88, v12, v93
	v_min_u32_e32 v12, v12, v93
	v_max_u32_e32 v93, v70, v90
	v_min_u32_e32 v70, v70, v90
	v_max_u32_e32 v90, v30, v94
	v_min_u32_e32 v30, v30, v94
	v_max_u32_e32 v94, v31, v26
	v_min_u32_e32 v26, v31, v26
	v_max_u32_e32 v99, v76, v13
	v_min_u32_e32 v13, v76, v13
	v_max_u32_e32 v76, v16, v86
	v_min_u32_e32 v16, v16, v86
	v_max_u32_e32 v86, v106, v83
	v_min_u32_e32 v83, v106, v83
	v_max_u32_e32 v106, v80, v22
	v_min_u32_e32 v22, v80, v22
	v_max_u32_e32 v80, v14, v89
	v_min_u32_e32 v14, v14, v89
	v_max_u32_e32 v89, v28, v24
	v_min_u32_e32 v24, v28, v24
	v_max_u32_e32 v28, v98, v91
	v_min_u32_e32 v91, v98, v91
	v_max_u32_e32 v98, v15, v18
	v_min_u32_e32 v15, v15, v18
	v_and_or_b32 v81, v81, s82, 51
	v_and_or_b32 v84, v84, s82, 64
	v_or_b32_e32 v87, 0x41, v87
	v_or_b32_e32 v19, 0x42, v19
	v_or_b32_e32 v92, 0x50, v92
	v_or_b32_e32 v21, 0x51, v21
	v_or_b32_e32 v95, 0x60, v95
	v_or_b32_e32 v23, 0x61, v23
	v_or_b32_e32 v97, 0x70, v97
	v_or_b32_e32 v25, 0x71, v25
	v_or_b32_e32 v27, 0x80, v27
	v_or_b32_e32 v29, 0x90, v29
	v_or_b32_e32 v20, 0xa0, v20
	v_or_b32_e32 v71, 0xb0, v71
	v_or_b32_e32 v73, 0xc0, v73
	v_or_b32_e32 v17, 0xd0, v17
	v_max_u32_e32 v31, v72, v78
	v_min_u32_e32 v72, v72, v78
	v_max_u32_e32 v78, v85, v82
	v_min_u32_e32 v82, v85, v82
	v_max_u32_e32 v85, v74, v79
	v_min_u32_e32 v74, v74, v79
	v_max_u32_e32 v79, v77, v75
	v_min_u32_e32 v75, v77, v75
	v_max_u32_e32 v77, v30, v12
	v_min_u32_e32 v12, v30, v12
	v_max_u32_e32 v30, v26, v70
	v_min_u32_e32 v26, v26, v70
	v_max_u32_e32 v70, v90, v88
	v_min_u32_e32 v88, v90, v88
	v_max_u32_e32 v90, v94, v93
	v_min_u32_e32 v93, v94, v93
	v_max_u32_e32 v18, v99, v86
	v_min_u32_e32 v86, v99, v86
	v_max_u32_e32 v99, v76, v106
	v_min_u32_e32 v76, v76, v106
	v_max_u32_e32 v106, v13, v83
	v_min_u32_e32 v13, v13, v83
	v_max_u32_e32 v83, v16, v22
	v_min_u32_e32 v16, v16, v22
	v_max_u32_e32 v22, v91, v14
	v_min_u32_e32 v14, v91, v14
	v_max_u32_e32 v91, v15, v24
	v_min_u32_e32 v15, v15, v24
	v_max_u32_e32 v24, v28, v80
	v_min_u32_e32 v28, v28, v80
	v_max_u32_e32 v80, v98, v89
	v_min_u32_e32 v89, v98, v89
	v_max_u32_e32 v94, v31, v78
	v_min_u32_e32 v31, v31, v78
	v_max_u32_e32 v78, v72, v82
	v_min_u32_e32 v72, v72, v82
	v_max_u32_e32 v82, v85, v79
	v_min_u32_e32 v79, v85, v79
	v_max_u32_e32 v85, v74, v75
	v_min_u32_e32 v74, v74, v75
	v_max_u32_e32 v75, v26, v12
	v_min_u32_e32 v12, v26, v12
	v_max_u32_e32 v26, v30, v77
	v_min_u32_e32 v30, v30, v77
	v_max_u32_e32 v77, v93, v88
	v_min_u32_e32 v88, v93, v88
	v_max_u32_e32 v93, v90, v70
	v_min_u32_e32 v70, v90, v70
	v_max_u32_e32 v98, v18, v99
	v_min_u32_e32 v18, v18, v99
	v_max_u32_e32 v99, v86, v76
	v_min_u32_e32 v76, v86, v76
	v_max_u32_e32 v86, v106, v83
	v_min_u32_e32 v83, v106, v83
	v_max_u32_e32 v106, v13, v16
	v_min_u32_e32 v13, v13, v16
	v_max_u32_e32 v16, v15, v14
	v_min_u32_e32 v14, v15, v14
	v_max_u32_e32 v15, v91, v22
	v_min_u32_e32 v22, v91, v22
	v_max_u32_e32 v91, v89, v28
	v_min_u32_e32 v28, v89, v28
	v_max_u32_e32 v89, v80, v24
	v_min_u32_e32 v24, v80, v24
	v_max_u32_e32 v114, v81, v84
	v_min_u32_e32 v81, v81, v84
	v_max_u32_e32 v84, v19, v87
	v_min_u32_e32 v19, v19, v87
	v_max_u32_e32 v87, v92, v21
	v_min_u32_e32 v21, v92, v21
	v_max_u32_e32 v92, v23, v95
	v_min_u32_e32 v23, v23, v95
	v_max_u32_e32 v95, v97, v25
	v_min_u32_e32 v25, v97, v25
	v_max_u32_e32 v97, v29, v27
	v_min_u32_e32 v27, v29, v27
	v_max_u32_e32 v29, v20, v71
	v_min_u32_e32 v20, v20, v71
	v_max_u32_e32 v71, v17, v73
	v_min_u32_e32 v17, v17, v73
	v_max_u32_e32 v90, v94, v12
	v_min_u32_e32 v12, v94, v12
	v_max_u32_e32 v94, v31, v75
	v_min_u32_e32 v31, v31, v75
	v_max_u32_e32 v75, v78, v30
	v_min_u32_e32 v30, v78, v30
	v_max_u32_e32 v78, v72, v26
	v_min_u32_e32 v26, v72, v26
; #define CE_DESC(a, b) do { const unsigned _h = max((a), (b)), _l = min((a), (b)); (a) = _h; (b) = _l; } while (0)
; __device__ __forceinline__ void sort16_desc(unsigned (&v)[16]) {
; #pragma unroll
;     for (int k = 2; k <= 16; k <<= 1)
; #pragma unroll
;         for (int j = k >> 1; j > 0; j >>= 1)
; #pragma unroll
;             for (int i = 0; i < 16; ++i) { const int p = i ^ j; if (p > i) { if ((i & k) == 0) CE_DESC(v[i], v[p]); else CE_DESC(v[p], v[i]); } }
; }
; __device__ __forceinline__ void merge16_desc(unsigned (&a)[16], const unsigned (&b)[16]) {
; #pragma unroll
;     for (int i = 0; i < 16; ++i) a[i] = max(a[i], b[15 - i]);
; #pragma unroll
;     for (int j = 8; j > 0; j >>= 1)
; #pragma unroll
;         for (int i = 0; i < 16; ++i) { const int p = i ^ j; if (p > i) CE_DESC(a[i], a[p]); }
; }
; __device__ __forceinline__ void phase_route(CArgs& A, int l, unsigned char* lds, int tid) {
;     ...
;             sort16_desc(L3); sort16_desc(g1); sort16_desc(g2); merge16_desc(L3, g1); merge16_desc(L3, g2);
	v_max_u32_e32 v72, v82, v88
	v_min_u32_e32 v82, v82, v88
	v_max_u32_e32 v88, v79, v77
	v_min_u32_e32 v77, v79, v77
	v_max_u32_e32 v79, v85, v70
	v_min_u32_e32 v70, v85, v70
	v_max_u32_e32 v85, v74, v93
	v_min_u32_e32 v74, v74, v93
	v_max_u32_e32 v80, v98, v14
	v_min_u32_e32 v14, v98, v14
	v_max_u32_e32 v98, v18, v16
	v_min_u32_e32 v16, v18, v16
	v_max_u32_e32 v18, v99, v22
	v_min_u32_e32 v22, v99, v22
	v_max_u32_e32 v99, v76, v15
	v_min_u32_e32 v15, v76, v15
	v_max_u32_e32 v76, v86, v28
	v_min_u32_e32 v28, v86, v28
	v_max_u32_e32 v86, v83, v91
	v_min_u32_e32 v83, v83, v91
	v_max_u32_e32 v91, v106, v24
	v_min_u32_e32 v24, v106, v24
	v_max_u32_e32 v106, v13, v89
	v_min_u32_e32 v13, v13, v89
	v_max_u32_e32 v73, v114, v19
	v_min_u32_e32 v19, v114, v19
	v_max_u32_e32 v114, v81, v84
	v_min_u32_e32 v81, v81, v84
	v_max_u32_e32 v84, v23, v87
	v_min_u32_e32 v23, v23, v87
	v_max_u32_e32 v87, v92, v21
	v_min_u32_e32 v21, v92, v21
	v_max_u32_e32 v92, v95, v27
	v_min_u32_e32 v27, v95, v27
	v_max_u32_e32 v95, v25, v97
	v_min_u32_e32 v25, v25, v97
	v_max_u32_e32 v97, v17, v29
	v_min_u32_e32 v17, v17, v29
	v_max_u32_e32 v29, v71, v20
	v_min_u32_e32 v20, v71, v20
	v_max_u32_e32 v93, v90, v72
	v_min_u32_e32 v72, v90, v72
	v_max_u32_e32 v90, v94, v88
	v_min_u32_e32 v88, v94, v88
	v_max_u32_e32 v94, v75, v79
	v_min_u32_e32 v75, v75, v79
	v_max_u32_e32 v79, v78, v85
	v_min_u32_e32 v78, v78, v85
	v_max_u32_e32 v85, v12, v82
	v_min_u32_e32 v12, v12, v82
	v_max_u32_e32 v82, v31, v77
	v_min_u32_e32 v31, v31, v77
	v_max_u32_e32 v77, v30, v70
	v_min_u32_e32 v30, v30, v70
	v_max_u32_e32 v70, v26, v74
	v_min_u32_e32 v26, v26, v74
	v_max_u32_e32 v89, v80, v76
	v_min_u32_e32 v76, v80, v76
	v_max_u32_e32 v80, v98, v86
	v_min_u32_e32 v86, v98, v86
	v_max_u32_e32 v98, v18, v91
	v_min_u32_e32 v18, v18, v91
	v_max_u32_e32 v91, v99, v106
	v_min_u32_e32 v99, v99, v106
	v_max_u32_e32 v106, v14, v28
	v_min_u32_e32 v14, v14, v28
	v_max_u32_e32 v28, v16, v83
	v_min_u32_e32 v16, v16, v83
	v_max_u32_e32 v83, v22, v24
	v_min_u32_e32 v22, v22, v24
	v_max_u32_e32 v24, v15, v13
	v_min_u32_e32 v13, v15, v13
	v_max_u32_e32 v71, v73, v114
	v_min_u32_e32 v73, v73, v114
	v_max_u32_e32 v114, v19, v81
	v_min_u32_e32 v19, v19, v81
	v_max_u32_e32 v81, v21, v23
	v_min_u32_e32 v21, v21, v23
	v_max_u32_e32 v23, v87, v84
	v_min_u32_e32 v84, v87, v84
	v_max_u32_e32 v87, v92, v95
	v_min_u32_e32 v92, v92, v95
	v_max_u32_e32 v95, v27, v25
	v_min_u32_e32 v25, v27, v25
	v_max_u32_e32 v27, v20, v17
	v_min_u32_e32 v17, v20, v17
	v_max_u32_e32 v20, v29, v97
	v_min_u32_e32 v29, v29, v97
	v_max_u32_e32 v74, v93, v94
	v_min_u32_e32 v93, v93, v94
	v_max_u32_e32 v94, v90, v79
	v_min_u32_e32 v79, v90, v79
	v_max_u32_e32 v90, v72, v75
	v_min_u32_e32 v72, v72, v75
	v_max_u32_e32 v75, v88, v78
	v_min_u32_e32 v78, v88, v78
	v_max_u32_e32 v88, v85, v77
	v_min_u32_e32 v77, v85, v77
	v_max_u32_e32 v85, v82, v70
	v_min_u32_e32 v70, v82, v70
	v_max_u32_e32 v82, v12, v30
	v_min_u32_e32 v12, v12, v30
	v_max_u32_e32 v30, v31, v26
	v_min_u32_e32 v26, v31, v26
	v_max_u32_e32 v15, v89, v98
	v_min_u32_e32 v89, v89, v98
	v_max_u32_e32 v98, v80, v91
	v_min_u32_e32 v80, v80, v91
	v_max_u32_e32 v91, v76, v18
	v_min_u32_e32 v18, v76, v18
	v_max_u32_e32 v76, v86, v99
	v_min_u32_e32 v86, v86, v99
	v_max_u32_e32 v99, v106, v83
	v_min_u32_e32 v83, v106, v83
	v_max_u32_e32 v106, v28, v24
	v_min_u32_e32 v24, v28, v24
	v_max_u32_e32 v28, v14, v22
	v_min_u32_e32 v14, v14, v22
	v_max_u32_e32 v22, v16, v13
	v_min_u32_e32 v13, v16, v13
	v_max_u32_e32 v97, v71, v21
	v_min_u32_e32 v21, v71, v21
	v_max_u32_e32 v71, v73, v81
	v_min_u32_e32 v73, v73, v81
	v_max_u32_e32 v81, v114, v84
	v_min_u32_e32 v84, v114, v84
	v_max_u32_e32 v114, v19, v23
	v_min_u32_e32 v19, v19, v23
	v_max_u32_e32 v23, v17, v87
	v_min_u32_e32 v17, v17, v87
	v_max_u32_e32 v87, v27, v92
	v_min_u32_e32 v27, v27, v92
	v_max_u32_e32 v92, v29, v95
	v_min_u32_e32 v29, v29, v95
	v_max_u32_e32 v95, v20, v25
	v_min_u32_e32 v20, v20, v25
	v_min_u32_e32 v31, v74, v94
	v_min_u32_e32 v96, v93, v79
	v_min_u32_e32 v100, v90, v75
	v_min_u32_e32 v101, v72, v78
	v_min_u32_e32 v102, v88, v85
	v_min_u32_e32 v103, v77, v70
	v_min_u32_e32 v104, v82, v30
	v_min_u32_e32 v105, v12, v26
	v_min_u32_e32 v16, v15, v98
	v_min_u32_e32 v107, v89, v80
	v_min_u32_e32 v108, v91, v76
	v_min_u32_e32 v109, v18, v86
	v_min_u32_e32 v110, v99, v106
	v_min_u32_e32 v111, v83, v24
	v_min_u32_e32 v112, v28, v22
	v_min_u32_e32 v113, v14, v13
	v_max_u32_e32 v25, v97, v81
	v_min_u32_e32 v81, v97, v81
	v_max_u32_e32 v97, v71, v114
	v_min_u32_e32 v71, v71, v114
	v_max_u32_e32 v114, v21, v84
	v_min_u32_e32 v21, v21, v84
	v_max_u32_e32 v84, v73, v19
	v_min_u32_e32 v19, v73, v19
	v_max_u32_e32 v73, v29, v17
	v_min_u32_e32 v17, v29, v17
	v_max_u32_e32 v29, v20, v27
	v_min_u32_e32 v20, v20, v27
	v_max_u32_e32 v27, v92, v23
	v_min_u32_e32 v23, v92, v23
	v_max_u32_e32 v92, v95, v87
	v_min_u32_e32 v87, v95, v87
	v_max_u32_e32 v95, v25, v97
	v_min_u32_e32 v25, v25, v97
	v_max_u32_e32 v97, v81, v71
	v_min_u32_e32 v71, v81, v71
	v_max_u32_e32 v81, v114, v84
	v_min_u32_e32 v84, v114, v84
	v_max_u32_e32 v114, v21, v19
	v_min_u32_e32 v19, v21, v19
	v_max_u32_e32 v21, v20, v17
	v_min_u32_e32 v17, v20, v17
	v_max_u32_e32 v20, v29, v73
	v_min_u32_e32 v29, v29, v73
	v_max_u32_e32 v73, v87, v23
	v_min_u32_e32 v23, v87, v23
	v_max_u32_e32 v87, v92, v27
	v_min_u32_e32 v27, v92, v27
	v_max3_u32 v74, v74, v94, v113
	v_max3_u32 v13, v31, v14, v13
	v_max3_u32 v14, v93, v79, v112
	v_max3_u32 v22, v96, v28, v22
	v_max3_u32 v28, v90, v75, v111
	v_max3_u32 v24, v100, v83, v24
	v_max3_u32 v31, v72, v78, v110
	v_max3_u32 v72, v101, v99, v106
; #define CE_DESC(a, b) do { const unsigned _h = max((a), (b)), _l = min((a), (b)); (a) = _h; (b) = _l; } while (0)
; __device__ __forceinline__ void merge16_desc(unsigned (&a)[16], const unsigned (&b)[16]) {
; #pragma unroll
;     for (int i = 0; i < 16; ++i) a[i] = max(a[i], b[15 - i]);
; #pragma unroll
;     for (int j = 8; j > 0; j >>= 1)
; #pragma unroll
;         for (int i = 0; i < 16; ++i) { const int p = i ^ j; if (p > i) CE_DESC(a[i], a[p]); }
; }
; __device__ __forceinline__ void phase_route(CArgs& A, int l, unsigned char* lds, int tid) {
;     ...
;             sort16_desc(L3); sort16_desc(g1); sort16_desc(g2); merge16_desc(L3, g1); merge16_desc(L3, g2);
	v_max3_u32 v75, v88, v85, v109
	v_max3_u32 v18, v102, v18, v86
	v_max3_u32 v70, v77, v70, v108
	v_max3_u32 v76, v103, v91, v76
	v_max3_u32 v30, v82, v30, v107
	v_max3_u32 v77, v104, v89, v80
	v_max3_u32 v12, v12, v26, v16
	v_max3_u32 v15, v105, v15, v98
	v_max_u32_e32 v92, v95, v17
	v_min_u32_e32 v17, v95, v17
	v_max_u32_e32 v95, v25, v21
	v_min_u32_e32 v21, v25, v21
	v_max_u32_e32 v25, v97, v29
	v_min_u32_e32 v29, v97, v29
	v_max_u32_e32 v97, v71, v20
	v_min_u32_e32 v20, v71, v20
	v_max_u32_e32 v71, v81, v23
	v_min_u32_e32 v23, v81, v23
	v_max_u32_e32 v81, v84, v73
	v_min_u32_e32 v73, v84, v73
	v_max_u32_e32 v84, v114, v27
	v_min_u32_e32 v27, v114, v27
	v_max_u32_e32 v114, v19, v87
	v_min_u32_e32 v19, v19, v87
	v_max_u32_e32 v16, v74, v75
	v_min_u32_e32 v26, v74, v75
	v_max_u32_e32 v74, v13, v18
	v_min_u32_e32 v13, v13, v18
	v_max_u32_e32 v18, v14, v70
	v_min_u32_e32 v14, v14, v70
	v_max_u32_e32 v70, v22, v76
	v_min_u32_e32 v22, v22, v76
	v_max_u32_e32 v75, v28, v30
	v_min_u32_e32 v28, v28, v30
	v_max_u32_e32 v30, v24, v77
	v_min_u32_e32 v24, v24, v77
	v_max_u32_e32 v76, v31, v12
	v_min_u32_e32 v12, v31, v12
	v_max_u32_e32 v31, v72, v15
	v_min_u32_e32 v15, v72, v15
	v_max_u32_e32 v87, v92, v71
	v_min_u32_e32 v71, v92, v71
	v_max_u32_e32 v92, v95, v81
	v_min_u32_e32 v81, v95, v81
	v_max_u32_e32 v95, v25, v84
	v_min_u32_e32 v25, v25, v84
	v_max_u32_e32 v84, v97, v114
	v_min_u32_e32 v97, v97, v114
	v_max_u32_e32 v114, v17, v23
	v_min_u32_e32 v17, v17, v23
	v_max_u32_e32 v23, v21, v73
	v_min_u32_e32 v21, v21, v73
	v_max_u32_e32 v73, v29, v27
	v_min_u32_e32 v27, v29, v27
	v_max_u32_e32 v29, v20, v19
	v_min_u32_e32 v19, v20, v19
	v_max_u32_e32 v72, v16, v75
	v_min_u32_e32 v16, v16, v75
	v_max_u32_e32 v75, v74, v30
	v_min_u32_e32 v30, v74, v30
	v_max_u32_e32 v74, v18, v76
	v_min_u32_e32 v18, v18, v76
	v_max_u32_e32 v76, v70, v31
	v_min_u32_e32 v31, v70, v31
	v_max_u32_e32 v70, v26, v28
	v_min_u32_e32 v26, v26, v28
	v_max_u32_e32 v28, v13, v24
	v_min_u32_e32 v13, v13, v24
	v_max_u32_e32 v24, v14, v12
	v_min_u32_e32 v12, v14, v12
	v_max_u32_e32 v14, v22, v15
	v_min_u32_e32 v15, v22, v15
	v_max_u32_e32 v20, v87, v95
	v_min_u32_e32 v87, v87, v95
	v_max_u32_e32 v95, v92, v84
	v_min_u32_e32 v84, v92, v84
	v_max_u32_e32 v92, v71, v25
	v_min_u32_e32 v25, v71, v25
	v_max_u32_e32 v71, v81, v97
	v_min_u32_e32 v81, v81, v97
	v_max_u32_e32 v97, v114, v73
	v_min_u32_e32 v73, v114, v73
	v_max_u32_e32 v114, v23, v29
	v_min_u32_e32 v23, v23, v29
	v_max_u32_e32 v29, v17, v27
	v_min_u32_e32 v17, v17, v27
	v_max_u32_e32 v27, v21, v19
	v_min_u32_e32 v19, v21, v19
	v_max_u32_e32 v22, v72, v74
	v_min_u32_e32 v72, v72, v74
	v_max_u32_e32 v74, v75, v76
	v_min_u32_e32 v75, v75, v76
	v_max_u32_e32 v76, v16, v18
	v_min_u32_e32 v16, v16, v18
	v_max_u32_e32 v18, v30, v31
	v_min_u32_e32 v30, v30, v31
	v_max_u32_e32 v31, v70, v24
	v_min_u32_e32 v24, v70, v24
	v_max_u32_e32 v70, v28, v14
	v_min_u32_e32 v14, v28, v14
	v_max_u32_e32 v28, v26, v12
	v_min_u32_e32 v12, v26, v12
	v_max_u32_e32 v26, v13, v15
	v_min_u32_e32 v13, v13, v15
	v_min_u32_e32 v21, v20, v95
	v_min_u32_e32 v115, v87, v84
	v_min_u32_e32 v116, v92, v71
	v_min_u32_e32 v117, v25, v81
	v_min_u32_e32 v118, v97, v114
	v_min_u32_e32 v119, v73, v23
	v_min_u32_e32 v120, v29, v27
	v_min_u32_e32 v121, v17, v19
	v_min_u32_e32 v15, v22, v74
	v_min_u32_e32 v77, v72, v75
	v_min_u32_e32 v78, v76, v18
	v_min_u32_e32 v79, v16, v30
	v_min_u32_e32 v80, v31, v70
	v_min_u32_e32 v82, v24, v14
	v_min_u32_e32 v83, v28, v26
	v_min_u32_e32 v85, v12, v13
	v_max3_u32 v22, v22, v74, v121
	v_max3_u32 v15, v15, v17, v19
	v_max3_u32 v17, v72, v75, v120
	v_max3_u32 v19, v77, v29, v27
	v_max3_u32 v18, v76, v18, v119
	v_max3_u32 v23, v78, v73, v23
	v_max3_u32 v16, v16, v30, v118
	v_max3_u32 v27, v79, v97, v114
	v_max3_u32 v29, v31, v70, v117
	v_max3_u32 v25, v80, v25, v81
	v_max3_u32 v14, v24, v14, v116
	v_max3_u32 v24, v82, v92, v71
	v_max3_u32 v26, v28, v26, v115
	v_max3_u32 v28, v83, v87, v84
	v_max3_u32 v12, v12, v13, v21
	v_max3_u32 v13, v85, v20, v95
	v_max_u32_e32 v20, v22, v29
	v_min_u32_e32 v21, v22, v29
	v_max_u32_e32 v22, v15, v25
	v_min_u32_e32 v15, v15, v25
	v_max_u32_e32 v25, v17, v14
	v_min_u32_e32 v14, v17, v14
	v_max_u32_e32 v17, v19, v24
	v_min_u32_e32 v19, v19, v24
	v_max_u32_e32 v24, v18, v26
	v_min_u32_e32 v18, v18, v26
	v_max_u32_e32 v26, v23, v28
	v_min_u32_e32 v23, v23, v28
	v_max_u32_e32 v28, v16, v12
	v_min_u32_e32 v12, v16, v12
	v_max_u32_e32 v16, v27, v13
	v_min_u32_e32 v13, v27, v13
	v_max_u32_e32 v27, v20, v24
	v_min_u32_e32 v20, v20, v24
	v_max_u32_e32 v24, v22, v26
	v_min_u32_e32 v22, v22, v26
	v_max_u32_e32 v26, v25, v28
	v_min_u32_e32 v25, v25, v28
	v_max_u32_e32 v28, v17, v16
	v_min_u32_e32 v16, v17, v16
	v_max_u32_e32 v17, v21, v18
	v_min_u32_e32 v18, v21, v18
	v_max_u32_e32 v21, v15, v23
	v_min_u32_e32 v15, v15, v23
	v_max_u32_e32 v23, v14, v12
	v_min_u32_e32 v12, v14, v12
	v_max_u32_e32 v14, v19, v13
	v_min_u32_e32 v13, v19, v13
	v_max_u32_e32 v19, v27, v26
	v_min_u32_e32 v26, v27, v26
	v_max_u32_e32 v27, v24, v28
	v_min_u32_e32 v24, v24, v28
	v_max_u32_e32 v28, v20, v25
	v_min_u32_e32 v20, v20, v25
	v_max_u32_e32 v25, v22, v16
	v_min_u32_e32 v16, v22, v16
	v_max_u32_e32 v22, v17, v23
	v_min_u32_e32 v17, v17, v23
	v_max_u32_e32 v23, v21, v14
	v_min_u32_e32 v14, v21, v14
	v_max_u32_e32 v21, v18, v12
	v_min_u32_e32 v12, v18, v12
	v_max_u32_e32 v18, v15, v13
	v_min_u32_e32 v13, v15, v13
	v_add_f32_e32 v10, v3, v10
	v_max_u32_e32 v80, v12, v13
	v_min_u32_e32 v12, v12, v13
	v_ashrrev_i32_e32 v13, 31, v10
	v_or_b32_e32 v13, 0x80000000, v13
	v_bitop3_b32 v10, v13, s82, v10 bitop3:0x48
	v_max_u32_e32 v15, v19, v27
; __device__ __forceinline__ unsigned ordf(float f) { unsigned u = __float_as_uint(f); return u ^ ((unsigned)((int)u >> 31) | 0x80000000u); }
; __device__ __forceinline__ float unordf(unsigned v) { return __uint_as_float(v ^ ((~(unsigned)((int)v >> 31)) | 0x80000000u)); }
; #define INSERT16(L, key) do { unsigned _k = (key); _Pragma("unroll") for (int _j = 0; _j < 16; ++_j) { const unsigned _hi = max(L[_j], _k); _k = min(L[_j], _k); L[_j] = _hi; } } while (0)
; __device__ __forceinline__ void phase_route(CArgs& A, int l, unsigned char* lds, int tid) {
;     ...
;             INSERT16(L3, (ordf(v1[CT.i[48]] + v2[CT.j[48]]) & ~0xFFu) | (unsigned)(CT.i[48] * 16 + CT.j[48]));
;             INSERT16(L3, (ordf(v1[CT.i[49]] + v2[CT.j[49]]) & ~0xFFu) | (unsigned)(CT.i[49] * 16 + CT.j[49]));
;             static_assert(CT.i[49] >= 0 && CT.i[50] < 0, "50 candidates");
;         }
;         float e[16], sum = 0.f; const float mx = unordf(L3[0] & ~0xFFu);
; #pragma unroll
;         for (int k = 0; k < 16; ++k) { e[k] = expf(unordf(L3[k] & ~0xFFu) - mx); sum += e[k]; }
	v_or_b32_e32 v10, 0xe0, v10
	v_min_u32_e32 v29, v19, v27
	v_max_u32_e32 v13, v15, v10
	v_min_u32_e32 v15, v15, v10
	v_max_u32_e32 v30, v26, v24
	v_min_u32_e32 v15, v29, v15
	v_min_u32_e32 v31, v26, v24
	v_med3_u32 v10, v19, v27, v10
	v_min_u32_e32 v27, v30, v15
	v_max_u32_e32 v70, v28, v25
	v_max_u32_e32 v19, v30, v15
	v_med3_u32 v15, v26, v24, v15
	v_min_u32_e32 v24, v31, v27
	v_min_u32_e32 v71, v28, v25
	v_min_u32_e32 v27, v70, v24
	v_max_u32_e32 v72, v20, v16
	v_max_u32_e32 v26, v70, v24
	v_med3_u32 v24, v28, v25, v24
	v_min_u32_e32 v25, v71, v27
	v_pk_add_f32 v[2:3], v[2:3], v[2:3] op_sel:[1,0] op_sel_hi:[0,1]
	v_min_u32_e32 v73, v20, v16
	v_min_u32_e32 v28, v72, v25
	v_ashrrev_i32_e32 v3, 31, v2
	v_max_u32_e32 v74, v22, v23
	v_med3_u32 v16, v20, v16, v25
	v_min_u32_e32 v20, v73, v28
	v_or_b32_e32 v3, 0x80000000, v3
	v_min_u32_e32 v75, v22, v23
	v_min_u32_e32 v28, v74, v20
	v_bitop3_b32 v2, v3, s82, v2 bitop3:0x48
	v_max_u32_e32 v76, v17, v14
	v_max_u32_e32 v27, v72, v25
	v_max_u32_e32 v25, v74, v20
	v_med3_u32 v20, v22, v23, v20
	v_min_u32_e32 v22, v75, v28
	v_or_b32_e32 v2, 0xf0, v2
	v_min_u32_e32 v77, v17, v14
	v_min_u32_e32 v28, v76, v22
	v_max_u32_e32 v73, v13, v2
	v_min_u32_e32 v2, v13, v2
	v_max_u32_e32 v78, v21, v18
	v_med3_u32 v14, v17, v14, v22
	v_min_u32_e32 v17, v77, v28
	v_max_u32_e32 v74, v10, v2
	v_min_u32_e32 v2, v10, v2
	v_min_u32_e32 v79, v21, v18
	v_max_u32_e32 v23, v76, v22
	v_min_u32_e32 v28, v78, v17
	v_max_u32_e32 v76, v19, v2
	v_min_u32_e32 v2, v19, v2
	v_max_u32_e32 v22, v78, v17
	v_med3_u32 v17, v21, v18, v17
	v_min_u32_e32 v18, v79, v28
	v_max_u32_e32 v78, v15, v2
	v_min_u32_e32 v2, v15, v2
	v_max_u32_e32 v21, v80, v18
	v_min_u32_e32 v18, v80, v18
	v_max_u32_e32 v80, v26, v2
	v_min_u32_e32 v2, v26, v2
	v_max_u32_e32 v82, v24, v2
	v_min_u32_e32 v2, v24, v2
	v_max_u32_e32 v83, v27, v2
	v_min_u32_e32 v2, v27, v2
	v_max_u32_e32 v84, v16, v2
	v_min_u32_e32 v2, v16, v2
	v_max_u32_e32 v75, v25, v2
	v_min_u32_e32 v2, v25, v2
	v_cmp_lt_i32_e32 vcc, -1, v73
	v_max_u32_e32 v77, v20, v2
	v_min_u32_e32 v2, v20, v2
	v_cndmask_b32_e64 v13, v182, -1, vcc
	v_max_u32_e32 v79, v23, v2
	v_min_u32_e32 v2, v23, v2
	v_bitop3_b32 v13, v13, v73, s82 bitop3:0x78
	v_max_u32_e32 v81, v14, v2
	v_min_u32_e32 v3, v14, v2
	v_sub_f32_e32 v14, v13, v13
	v_min_u32_e32 v10, v22, v3
	v_mul_f32_e32 v15, 0x3fb8aa3b, v14
	v_max_u32_e32 v2, v22, v3
	v_max_u32_e32 v3, v17, v10
	v_min_u32_e32 v10, v17, v10
	v_fma_f32 v16, v14, s83, -v15
	v_rndne_f32_e32 v17, v15
	v_fmac_f32_e32 v16, 0x32a5705f, v14
	v_sub_f32_e32 v15, v15, v17
	v_add_f32_e32 v15, v15, v16
	v_exp_f32_e32 v15, v15
	v_cvt_i32_f32_e32 v16, v17
	v_max_u32_e32 v85, v21, v10
	v_min_u32_e32 v10, v21, v10
	v_cmp_lt_i32_e32 vcc, -1, v74
	v_max3_u32 v86, v12, v18, v10
	v_ldexp_f32 v10, v15, v16
	v_cndmask_b32_e64 v12, v182, -1, vcc
	v_bitop3_b32 v12, v12, v74, s82 bitop3:0x78
	v_sub_f32_e32 v12, v12, v13
	v_mul_f32_e32 v15, 0x3fb8aa3b, v12
	v_fma_f32 v16, v12, s83, -v15
	v_rndne_f32_e32 v17, v15
	v_fmac_f32_e32 v16, 0x32a5705f, v12
	v_sub_f32_e32 v15, v15, v17
	v_add_f32_e32 v15, v15, v16
	v_exp_f32_e32 v15, v15
	v_cvt_i32_f32_e32 v17, v17
	v_cmp_ngt_f32_e32 vcc, s76, v14
	v_and_b32_e32 v6, 0x7f, v6
	v_and_b32_e32 v45, 0x7f, v45
	v_cndmask_b32_e32 v10, 0, v10, vcc
	v_cmp_nlt_f32_e32 vcc, s77, v14
	v_and_b32_e32 v46, 0x7f, v46
	v_and_b32_e32 v48, 0x7f, v48
	v_cndmask_b32_e32 v16, v181, v10, vcc
	v_ldexp_f32 v10, v15, v17
	v_cmp_ngt_f32_e32 vcc, s76, v12
	v_and_b32_e32 v49, 0x7f, v49
	v_and_b32_e32 v50, 0x7f, v50
	v_cndmask_b32_e32 v10, 0, v10, vcc
	v_cmp_lt_i32_e32 vcc, -1, v76
	v_and_b32_e32 v51, 0x7f, v51
	v_and_b32_e32 v52, 0x7f, v52
	v_cndmask_b32_e64 v14, v182, -1, vcc
	v_bitop3_b32 v14, v14, v76, s82 bitop3:0x78
	v_sub_f32_e32 v14, v14, v13
	v_mul_f32_e32 v15, 0x3fb8aa3b, v14
	v_fma_f32 v17, v14, s83, -v15
	v_rndne_f32_e32 v18, v15
	v_fmac_f32_e32 v17, 0x32a5705f, v14
	v_sub_f32_e32 v15, v15, v18
	v_add_f32_e32 v15, v15, v17
	v_exp_f32_e32 v15, v15
	v_cvt_i32_f32_e32 v18, v18
	v_cmp_nlt_f32_e32 vcc, s77, v12
	v_and_b32_e32 v53, 0x7f, v53
	v_and_b32_e32 v67, 0x7f, v67
	v_cndmask_b32_e32 v17, v181, v10, vcc
	v_ldexp_f32 v12, v15, v18
	v_cmp_ngt_f32_e32 vcc, s76, v14
	v_add_f32_e32 v10, v16, v17
	v_and_b32_e32 v69, 0x7f, v69
	v_cndmask_b32_e32 v12, 0, v12, vcc
	v_cmp_lt_i32_e32 vcc, -1, v78
	v_and_b32_e32 v71, 0x7f, v9
	v_and_b32_e32 v72, 0x7f, v4
	v_cndmask_b32_e64 v15, v182, -1, vcc
	v_bitop3_b32 v15, v15, v78, s82 bitop3:0x78
	v_sub_f32_e32 v15, v15, v13
	v_mul_f32_e32 v18, 0x3fb8aa3b, v15
	v_fma_f32 v19, v15, s83, -v18
	v_rndne_f32_e32 v20, v18
	v_fmac_f32_e32 v19, 0x32a5705f, v15
	v_sub_f32_e32 v18, v18, v20
	v_add_f32_e32 v18, v18, v19
	v_exp_f32_e32 v19, v18
	v_cvt_i32_f32_e32 v20, v20
	v_cmp_nlt_f32_e32 vcc, s77, v14
	s_nop 1
	v_cndmask_b32_e32 v18, v181, v12, vcc
	v_ldexp_f32 v12, v19, v20
	v_cmp_ngt_f32_e32 vcc, s76, v15
	v_add_f32_e32 v10, v10, v18
	s_nop 0
	v_cndmask_b32_e32 v12, 0, v12, vcc
	v_cmp_lt_i32_e32 vcc, -1, v80
	s_nop 1
	v_cndmask_b32_e64 v14, v182, -1, vcc
	v_bitop3_b32 v14, v14, v80, s82 bitop3:0x78
	v_sub_f32_e32 v14, v14, v13
	v_mul_f32_e32 v19, 0x3fb8aa3b, v14
	v_fma_f32 v20, v14, s83, -v19
	v_rndne_f32_e32 v21, v19
	v_fmac_f32_e32 v20, 0x32a5705f, v14
	v_sub_f32_e32 v19, v19, v21
	v_add_f32_e32 v19, v19, v20
	v_exp_f32_e32 v20, v19
	v_cvt_i32_f32_e32 v21, v21
	v_cmp_nlt_f32_e32 vcc, s77, v15
	s_nop 1
	v_cndmask_b32_e32 v19, v181, v12, vcc
	v_ldexp_f32 v12, v20, v21
	v_cmp_ngt_f32_e32 vcc, s76, v14
	v_add_f32_e32 v10, v10, v19
	s_nop 0
	v_cndmask_b32_e32 v12, 0, v12, vcc
	v_cmp_lt_i32_e32 vcc, -1, v82
	s_nop 1
	v_cndmask_b32_e64 v15, v182, -1, vcc
; __device__ __forceinline__ float unordf(unsigned v) { return __uint_as_float(v ^ ((~(unsigned)((int)v >> 31)) | 0x80000000u)); }
; __device__ __forceinline__ void phase_route(CArgs& A, int l, unsigned char* lds, int tid) {
;     ...
;         float e[16], sum = 0.f; const float mx = unordf(L3[0] & ~0xFFu);
; #pragma unroll
;         for (int k = 0; k < 16; ++k) { e[k] = expf(unordf(L3[k] & ~0xFFu) - mx); sum += e[k]; }
	v_bitop3_b32 v15, v15, v82, s82 bitop3:0x78
	v_sub_f32_e32 v15, v15, v13
	v_mul_f32_e32 v20, 0x3fb8aa3b, v15
	v_fma_f32 v21, v15, s83, -v20
	v_rndne_f32_e32 v22, v20
	v_fmac_f32_e32 v21, 0x32a5705f, v15
	v_sub_f32_e32 v20, v20, v22
	v_add_f32_e32 v20, v20, v21
	v_exp_f32_e32 v21, v20
	v_cvt_i32_f32_e32 v22, v22
	v_cmp_nlt_f32_e32 vcc, s77, v14
	s_nop 1
	v_cndmask_b32_e32 v20, v181, v12, vcc
	v_ldexp_f32 v12, v21, v22
	v_cmp_ngt_f32_e32 vcc, s76, v15
	v_add_f32_e32 v10, v10, v20
	s_nop 0
	v_cndmask_b32_e32 v12, 0, v12, vcc
	v_cmp_lt_i32_e32 vcc, -1, v83
	s_nop 1
	v_cndmask_b32_e64 v14, v182, -1, vcc
	v_bitop3_b32 v14, v14, v83, s82 bitop3:0x78
	v_sub_f32_e32 v14, v14, v13
	v_mul_f32_e32 v21, 0x3fb8aa3b, v14
	v_fma_f32 v22, v14, s83, -v21
	v_rndne_f32_e32 v23, v21
	v_fmac_f32_e32 v22, 0x32a5705f, v14
	v_sub_f32_e32 v21, v21, v23
	v_add_f32_e32 v21, v21, v22
	v_exp_f32_e32 v22, v21
	v_cvt_i32_f32_e32 v23, v23
	v_cmp_nlt_f32_e32 vcc, s77, v15
	s_nop 1
	v_cndmask_b32_e32 v21, v181, v12, vcc
	v_ldexp_f32 v12, v22, v23
	v_cmp_ngt_f32_e32 vcc, s76, v14
	v_add_f32_e32 v10, v10, v21
	s_nop 0
	v_cndmask_b32_e32 v12, 0, v12, vcc
	v_cmp_lt_i32_e32 vcc, -1, v84
	s_nop 1
	v_cndmask_b32_e64 v15, v182, -1, vcc
	v_bitop3_b32 v15, v15, v84, s82 bitop3:0x78
	v_sub_f32_e32 v15, v15, v13
	v_mul_f32_e32 v22, 0x3fb8aa3b, v15
	v_fma_f32 v23, v15, s83, -v22
	v_rndne_f32_e32 v24, v22
	v_fmac_f32_e32 v23, 0x32a5705f, v15
	v_sub_f32_e32 v22, v22, v24
	v_add_f32_e32 v22, v22, v23
	v_exp_f32_e32 v23, v22
	v_cvt_i32_f32_e32 v24, v24
	v_cmp_nlt_f32_e32 vcc, s77, v14
	s_nop 1
	v_cndmask_b32_e32 v22, v181, v12, vcc
	v_ldexp_f32 v12, v23, v24
	v_cmp_ngt_f32_e32 vcc, s76, v15
	v_add_f32_e32 v10, v10, v22
	s_nop 0
	v_cndmask_b32_e32 v12, 0, v12, vcc
	v_cmp_lt_i32_e32 vcc, -1, v75
	s_nop 1
	v_cndmask_b32_e64 v14, v182, -1, vcc
	v_bitop3_b32 v14, v14, v75, s82 bitop3:0x78
	v_sub_f32_e32 v14, v14, v13
	v_mul_f32_e32 v23, 0x3fb8aa3b, v14
	v_fma_f32 v24, v14, s83, -v23
	v_rndne_f32_e32 v25, v23
	v_fmac_f32_e32 v24, 0x32a5705f, v14
	v_sub_f32_e32 v23, v23, v25
	v_add_f32_e32 v23, v23, v24
	v_exp_f32_e32 v24, v23
	v_cvt_i32_f32_e32 v25, v25
	v_cmp_nlt_f32_e32 vcc, s77, v15
	s_nop 1
	v_cndmask_b32_e32 v23, v181, v12, vcc
	v_ldexp_f32 v12, v24, v25
	v_cmp_ngt_f32_e32 vcc, s76, v14
	v_add_f32_e32 v10, v10, v23
	s_nop 0
	v_cndmask_b32_e32 v12, 0, v12, vcc
	v_cmp_lt_i32_e32 vcc, -1, v77
	s_nop 1
	v_cndmask_b32_e64 v15, v182, -1, vcc
	v_bitop3_b32 v15, v15, v77, s82 bitop3:0x78
	v_sub_f32_e32 v15, v15, v13
	v_mul_f32_e32 v24, 0x3fb8aa3b, v15
	v_fma_f32 v25, v15, s83, -v24
	v_rndne_f32_e32 v26, v24
	v_fmac_f32_e32 v25, 0x32a5705f, v15
	v_sub_f32_e32 v24, v24, v26
	v_add_f32_e32 v24, v24, v25
	v_exp_f32_e32 v25, v24
	v_cvt_i32_f32_e32 v26, v26
	v_cmp_nlt_f32_e32 vcc, s77, v14
	s_nop 1
	v_cndmask_b32_e32 v24, v181, v12, vcc
	v_ldexp_f32 v12, v25, v26
	v_cmp_ngt_f32_e32 vcc, s76, v15
	v_add_f32_e32 v10, v10, v24
	s_nop 0
	v_cndmask_b32_e32 v12, 0, v12, vcc
	v_cmp_lt_i32_e32 vcc, -1, v79
	s_nop 1
	v_cndmask_b32_e64 v14, v182, -1, vcc
	v_bitop3_b32 v14, v14, v79, s82 bitop3:0x78
	v_sub_f32_e32 v14, v14, v13
	v_mul_f32_e32 v25, 0x3fb8aa3b, v14
	v_fma_f32 v26, v14, s83, -v25
	v_rndne_f32_e32 v27, v25
	v_fmac_f32_e32 v26, 0x32a5705f, v14
	v_sub_f32_e32 v25, v25, v27
	v_add_f32_e32 v25, v25, v26
	v_exp_f32_e32 v26, v25
	v_cvt_i32_f32_e32 v27, v27
	v_cmp_nlt_f32_e32 vcc, s77, v15
	s_nop 1
	v_cndmask_b32_e32 v25, v181, v12, vcc
	v_ldexp_f32 v12, v26, v27
	v_cmp_ngt_f32_e32 vcc, s76, v14
	v_add_f32_e32 v10, v10, v25
	s_nop 0
	v_cndmask_b32_e32 v12, 0, v12, vcc
	v_cmp_lt_i32_e32 vcc, -1, v81
	s_nop 1
	v_cndmask_b32_e64 v15, v182, -1, vcc
	v_bitop3_b32 v15, v15, v81, s82 bitop3:0x78
	v_sub_f32_e32 v15, v15, v13
	v_mul_f32_e32 v26, 0x3fb8aa3b, v15
	v_fma_f32 v27, v15, s83, -v26
	v_rndne_f32_e32 v28, v26
	v_fmac_f32_e32 v27, 0x32a5705f, v15
	v_sub_f32_e32 v26, v26, v28
	v_add_f32_e32 v26, v26, v27
	v_exp_f32_e32 v27, v26
	v_cvt_i32_f32_e32 v28, v28
	v_cmp_nlt_f32_e32 vcc, s77, v14
	s_nop 1
	v_cndmask_b32_e32 v26, v181, v12, vcc
	v_ldexp_f32 v12, v27, v28
	v_cmp_ngt_f32_e32 vcc, s76, v15
	v_add_f32_e32 v10, v10, v26
	s_nop 0
	v_cndmask_b32_e32 v12, 0, v12, vcc
	v_cmp_lt_i32_e32 vcc, -1, v2
	s_nop 1
	v_cndmask_b32_e64 v14, v182, -1, vcc
	v_bitop3_b32 v14, v14, v2, s82 bitop3:0x78
	v_sub_f32_e32 v14, v14, v13
	v_mul_f32_e32 v27, 0x3fb8aa3b, v14
	v_fma_f32 v28, v14, s83, -v27
	v_rndne_f32_e32 v29, v27
	v_fmac_f32_e32 v28, 0x32a5705f, v14
	v_sub_f32_e32 v27, v27, v29
	v_add_f32_e32 v27, v27, v28
	v_exp_f32_e32 v28, v27
	v_cvt_i32_f32_e32 v29, v29
	v_cmp_nlt_f32_e32 vcc, s77, v15
	s_nop 1
	v_cndmask_b32_e32 v27, v181, v12, vcc
	v_ldexp_f32 v12, v28, v29
	v_cmp_ngt_f32_e32 vcc, s76, v14
	v_add_f32_e32 v10, v10, v27
	s_nop 0
	v_cndmask_b32_e32 v12, 0, v12, vcc
	v_cmp_lt_i32_e32 vcc, -1, v3
	s_nop 1
	v_cndmask_b32_e64 v15, v182, -1, vcc
	v_bitop3_b32 v15, v15, v3, s82 bitop3:0x78
	v_sub_f32_e32 v15, v15, v13
	v_mul_f32_e32 v28, 0x3fb8aa3b, v15
	v_fma_f32 v29, v15, s83, -v28
	v_rndne_f32_e32 v30, v28
	v_fmac_f32_e32 v29, 0x32a5705f, v15
	v_sub_f32_e32 v28, v28, v30
	v_add_f32_e32 v28, v28, v29
	v_exp_f32_e32 v29, v28
	v_cvt_i32_f32_e32 v30, v30
	v_cmp_nlt_f32_e32 vcc, s77, v14
	s_nop 1
	v_cndmask_b32_e32 v28, v181, v12, vcc
	v_ldexp_f32 v12, v29, v30
	v_cmp_ngt_f32_e32 vcc, s76, v15
	v_add_f32_e32 v10, v10, v28
	s_nop 0
	v_cndmask_b32_e32 v12, 0, v12, vcc
	v_cmp_lt_i32_e32 vcc, -1, v85
	s_nop 1
	v_cndmask_b32_e64 v14, v182, -1, vcc
	v_bitop3_b32 v14, v14, v85, s82 bitop3:0x78
	v_sub_f32_e32 v14, v14, v13
	v_mul_f32_e32 v29, 0x3fb8aa3b, v14
	v_fma_f32 v30, v14, s83, -v29
	v_rndne_f32_e32 v31, v29
; __device__ __forceinline__ float unordf(unsigned v) { return __uint_as_float(v ^ ((~(unsigned)((int)v >> 31)) | 0x80000000u)); }
; __device__ __forceinline__ void phase_route(CArgs& A, int l, unsigned char* lds, int tid) {
;     ...
;         float e[16], sum = 0.f; const float mx = unordf(L3[0] & ~0xFFu);
; #pragma unroll
;         for (int k = 0; k < 16; ++k) { e[k] = expf(unordf(L3[k] & ~0xFFu) - mx); sum += e[k]; }
;         const float inv = 1.f / sum;
;         int ex[16];
; #pragma unroll
;         for (int k = 0; k < 16; ++k) { const unsigned ci = L3[k] & 0xFFu, i = ci >> 4, j = ci & 15u; unsigned e1 = 0u, e2 = 0u;
; #pragma unroll
;             for (int ii = 0; ii < 16; ++ii) { e1 = (i == (unsigned)ii) ? (L1[ii] & 0x7Fu) : e1; e2 = (j == (unsigned)ii) ? (L2[ii] & 0x7Fu) : e2; }
;             ex[k] = (int)(e1 * 128u + e2); e[k] *= inv; }
;         int* ip = IDX + (size_t)t * 128 + hd * 16; float* gp = GATE + (size_t)t * 128 + hd * 16;
;         if (hf == 0) {
;             *(int4*)ip = make_int4(ex[0], ex[1], ex[2], ex[3]); *(int4*)(ip + 4) = make_int4(ex[4], ex[5], ex[6], ex[7]);
;             *(f32x4*)gp = (f32x4){e[0], e[1], e[2], e[3]}; *(f32x4*)(gp + 4) = (f32x4){e[4], e[5], e[6], e[7]};
;         } else {
;             *(int4*)(ip + 8) = make_int4(ex[8], ex[9], ex[10], ex[11]); *(int4*)(ip + 12) = make_int4(ex[12], ex[13], ex[14], ex[15]);
;             *(f32x4*)(gp + 8) = (f32x4){e[8], e[9], e[10], e[11]}; *(f32x4*)(gp + 12) = (f32x4){e[12], e[13], e[14], e[15]};
	v_fmac_f32_e32 v30, 0x32a5705f, v14
	v_sub_f32_e32 v29, v29, v31
	v_add_f32_e32 v29, v29, v30
	v_exp_f32_e32 v30, v29
	v_cvt_i32_f32_e32 v31, v31
	v_cmp_nlt_f32_e32 vcc, s77, v15
	s_nop 1
	v_cndmask_b32_e32 v29, v181, v12, vcc
	v_ldexp_f32 v12, v30, v31
	v_cmp_ngt_f32_e32 vcc, s76, v14
	v_add_f32_e32 v10, v10, v29
	s_nop 0
	v_cndmask_b32_e32 v12, 0, v12, vcc
	v_cmp_lt_i32_e32 vcc, -1, v86
	s_nop 1
	v_cndmask_b32_e64 v15, v182, -1, vcc
	v_bitop3_b32 v15, v15, v86, s82 bitop3:0x78
	v_sub_f32_e32 v13, v15, v13
	v_mul_f32_e32 v15, 0x3fb8aa3b, v13
	v_fma_f32 v30, v13, s83, -v15
	v_rndne_f32_e32 v31, v15
	v_fmac_f32_e32 v30, 0x32a5705f, v13
	v_sub_f32_e32 v15, v15, v31
	v_add_f32_e32 v15, v15, v30
	v_exp_f32_e32 v15, v15
	v_cvt_i32_f32_e32 v31, v31
	v_cmp_nlt_f32_e32 vcc, s77, v14
	s_nop 1
	v_cndmask_b32_e32 v30, v181, v12, vcc
	v_ldexp_f32 v12, v15, v31
	v_cmp_ngt_f32_e32 vcc, s76, v13
	v_add_f32_e32 v10, v10, v30
	s_nop 0
	v_cndmask_b32_e32 v12, 0, v12, vcc
	v_cmp_nlt_f32_e32 vcc, s77, v13
	s_nop 1
	v_cndmask_b32_e32 v31, v181, v12, vcc
	v_add_f32_e32 v10, v10, v31
	v_div_scale_f32 v12, s[0:1], v10, v10, 1.0
	v_rcp_f32_e32 v13, v12
	s_nop 0
	v_fma_f32 v14, -v12, v13, 1.0
	v_fmac_f32_e32 v13, v14, v13
	v_div_scale_f32 v14, vcc, 1.0, v10, 1.0
	v_mul_f32_e32 v15, v14, v13
	v_fma_f32 v70, -v12, v15, v14
	v_fmac_f32_e32 v15, v70, v13
	v_fma_f32 v12, -v12, v15, v14
	v_div_fmas_f32 v12, v12, v13, v15
	v_div_fixup_f32 v10, v12, v10, 1.0
	v_lshlrev_b64 v[12:13], 9, v[60:61]
	v_lshl_add_u64 v[14:15], v[54:55], 0, v[12:13]
	v_lshl_add_u64 v[12:13], v[56:57], 0, v[12:13]
	v_and_b32_e32 v60, 0x7f, v68
	v_and_b32_e32 v61, 0x7f, v8
	v_and_b32_e32 v68, 0x7f, v7
	v_and_b32_e32 v70, 0x7f, v5
	s_and_saveexec_b64 s[0:1], s[40:41]
	s_xor_b64 s[4:5], exec, s[0:1]
	s_cbranch_execz .LBB0_137
	v_and_b32_e32 v4, 15, v86
	v_mov_b64_e32 v[22:23], v[30:31]
	v_mov_b64_e32 v[20:21], v[28:29]
	v_mov_b32_e32 v241, 0x0c0c0c00
	v_lshl_or_b32 v230, v44, 8, v45
	v_lshl_or_b32 v230, v43, 16, v230
	v_lshl_or_b32 v230, v42, 24, v230
	v_lshl_or_b32 v231, v40, 8, v41
	v_lshl_or_b32 v231, v39, 16, v231
	v_lshl_or_b32 v231, v38, 24, v231
	v_lshl_or_b32 v232, v36, 8, v37
	v_lshl_or_b32 v232, v35, 16, v232
	v_lshl_or_b32 v232, v34, 24, v232
	v_lshl_or_b32 v233, v32, 8, v33
	v_lshl_or_b32 v233, v11, 16, v233
	v_lshl_or_b32 v233, v6, 24, v233
	v_and_or_b32 v238, v4, 7, v241
	v_bfe_i32 v239, v4, 3, 1
	v_perm_b32 v240, v231, v230, v238
	v_perm_b32 v238, v233, v232, v238
	v_bfi_b32 v5, v239, v238, v240
	v_bfe_u32 v4, v86, 4, 4
	s_nop 0
	v_lshl_or_b32 v234, v71, 8, v72
	v_lshl_or_b32 v234, v70, 16, v234
	v_lshl_or_b32 v234, v69, 24, v234
	v_lshl_or_b32 v235, v67, 8, v68
	v_lshl_or_b32 v235, v61, 16, v235
	v_lshl_or_b32 v235, v60, 24, v235
	v_lshl_or_b32 v236, v52, 8, v53
	v_lshl_or_b32 v236, v51, 16, v236
	v_lshl_or_b32 v236, v50, 24, v236
	v_lshl_or_b32 v237, v48, 8, v49
	v_lshl_or_b32 v237, v47, 16, v237
	v_lshl_or_b32 v237, v46, 24, v237
	v_and_or_b32 v238, v4, 7, v241
	v_bfe_i32 v239, v4, 3, 1
	v_perm_b32 v240, v235, v234, v238
	v_perm_b32 v238, v237, v236, v238
	v_bfi_b32 v16, v239, v238, v240
	v_bfe_u32 v4, v85, 4, 4
	s_nop 0
	v_lshl_add_u32 v5, v16, 7, v5
	s_nop 0
	v_and_or_b32 v238, v4, 7, v241
	v_bfe_i32 v239, v4, 3, 1
	v_perm_b32 v240, v235, v234, v238
	v_perm_b32 v238, v237, v236, v238
	v_bfi_b32 v4, v239, v238, v240
	v_and_b32_e32 v7, 15, v85
	v_and_or_b32 v238, v7, 7, v241
	v_bfe_i32 v239, v7, 3, 1
	v_perm_b32 v240, v231, v230, v238
	v_perm_b32 v238, v233, v232, v238
	v_bfi_b32 v7, v239, v238, v240
	v_lshl_add_u32 v4, v4, 7, v7
	v_bfe_u32 v7, v3, 4, 4
	v_and_b32_e32 v3, 15, v3
	s_nop 0
	v_and_or_b32 v238, v7, 7, v241
	v_bfe_i32 v239, v7, 3, 1
	v_perm_b32 v240, v235, v234, v238
	v_perm_b32 v238, v237, v236, v238
	v_bfi_b32 v7, v239, v238, v240
	v_cmp_eq_u32_e32 vcc, 0, v3
	v_cmp_eq_u32_e64 s[100:101], 1, v3
	v_cmp_eq_u32_e64 s[98:99], 2, v3
	v_cndmask_b32_e32 v8, 0, v45, vcc
	v_cmp_eq_u32_e32 vcc, 3, v3
	v_cndmask_b32_e64 v8, v8, v44, s[100:101]
	v_cmp_eq_u32_e64 s[100:101], 4, v3
	v_cndmask_b32_e64 v8, v8, v43, s[98:99]
	v_cmp_eq_u32_e64 s[98:99], 5, v3
	v_cndmask_b32_e32 v8, v8, v42, vcc
	v_cmp_eq_u32_e32 vcc, 6, v3
	v_cndmask_b32_e64 v8, v8, v41, s[100:101]
	v_cmp_eq_u32_e64 s[100:101], 7, v3
	v_cndmask_b32_e64 v8, v8, v40, s[98:99]
	v_cmp_eq_u32_e64 s[98:99], 8, v3
	v_cndmask_b32_e32 v8, v8, v39, vcc
	v_cmp_eq_u32_e32 vcc, 9, v3
	v_cndmask_b32_e64 v8, v8, v38, s[100:101]
	v_cmp_eq_u32_e64 s[100:101], 10, v3
	v_cndmask_b32_e64 v8, v8, v37, s[98:99]
	v_cmp_eq_u32_e64 s[98:99], 11, v3
	v_cndmask_b32_e32 v8, v8, v36, vcc
	v_cmp_eq_u32_e32 vcc, 12, v3
	v_cndmask_b32_e64 v8, v8, v35, s[100:101]
	v_cmp_eq_u32_e64 s[100:101], 13, v3
	v_cndmask_b32_e64 v8, v8, v34, s[98:99]
	v_cmp_eq_u32_e64 s[98:99], 14, v3
	v_cndmask_b32_e32 v8, v8, v33, vcc
	v_cmp_eq_u32_e32 vcc, 15, v3
	v_cndmask_b32_e64 v8, v8, v32, s[100:101]
	v_cndmask_b32_e64 v8, v8, v11, s[98:99]
	v_cndmask_b32_e32 v3, v8, v6, vcc
	v_lshl_add_u32 v3, v7, 7, v3
	v_bfe_u32 v7, v2, 4, 4
	v_and_b32_e32 v2, 15, v2
	s_nop 0
	v_and_or_b32 v238, v7, 7, v241
	v_bfe_i32 v239, v7, 3, 1
	v_perm_b32 v240, v235, v234, v238
	v_perm_b32 v238, v237, v236, v238
	v_bfi_b32 v7, v239, v238, v240
	v_cmp_eq_u32_e32 vcc, 0, v2
	v_cmp_eq_u32_e64 s[100:101], 1, v2
	v_cmp_eq_u32_e64 s[98:99], 2, v2
	v_cndmask_b32_e32 v8, 0, v45, vcc
	v_cmp_eq_u32_e32 vcc, 3, v2
	v_cndmask_b32_e64 v8, v8, v44, s[100:101]
	v_cmp_eq_u32_e64 s[100:101], 4, v2
	v_cndmask_b32_e64 v8, v8, v43, s[98:99]
	v_cmp_eq_u32_e64 s[98:99], 5, v2
	v_cndmask_b32_e32 v8, v8, v42, vcc
	v_cmp_eq_u32_e32 vcc, 6, v2
	v_cndmask_b32_e64 v8, v8, v41, s[100:101]
	v_cmp_eq_u32_e64 s[100:101], 7, v2
; __device__ __forceinline__ void phase_route(CArgs& A, int l, unsigned char* lds, int tid) {
;     ...
;         int ex[16];
; #pragma unroll
;         for (int k = 0; k < 16; ++k) { const unsigned ci = L3[k] & 0xFFu, i = ci >> 4, j = ci & 15u; unsigned e1 = 0u, e2 = 0u;
; #pragma unroll
;             for (int ii = 0; ii < 16; ++ii) { e1 = (i == (unsigned)ii) ? (L1[ii] & 0x7Fu) : e1; e2 = (j == (unsigned)ii) ? (L2[ii] & 0x7Fu) : e2; }
;             ex[k] = (int)(e1 * 128u + e2); e[k] *= inv; }
;         int* ip = IDX + (size_t)t * 128 + hd * 16; float* gp = GATE + (size_t)t * 128 + hd * 16;
;         if (hf == 0) {
;             *(int4*)ip = make_int4(ex[0], ex[1], ex[2], ex[3]); *(int4*)(ip + 4) = make_int4(ex[4], ex[5], ex[6], ex[7]);
;             *(f32x4*)gp = (f32x4){e[0], e[1], e[2], e[3]}; *(f32x4*)(gp + 4) = (f32x4){e[4], e[5], e[6], e[7]};
;         } else {
;             *(int4*)(ip + 8) = make_int4(ex[8], ex[9], ex[10], ex[11]); *(int4*)(ip + 12) = make_int4(ex[12], ex[13], ex[14], ex[15]);
;             *(f32x4*)(gp + 8) = (f32x4){e[8], e[9], e[10], e[11]}; *(f32x4*)(gp + 12) = (f32x4){e[12], e[13], e[14], e[15]};
	v_cndmask_b32_e64 v8, v8, v40, s[98:99]
	v_cmp_eq_u32_e64 s[98:99], 8, v2
	v_cndmask_b32_e32 v8, v8, v39, vcc
	v_cmp_eq_u32_e32 vcc, 9, v2
	v_cndmask_b32_e64 v8, v8, v38, s[100:101]
	v_cmp_eq_u32_e64 s[100:101], 10, v2
	v_cndmask_b32_e64 v8, v8, v37, s[98:99]
	v_cmp_eq_u32_e64 s[98:99], 11, v2
	v_cndmask_b32_e32 v8, v8, v36, vcc
	v_cmp_eq_u32_e32 vcc, 12, v2
	v_cndmask_b32_e64 v8, v8, v35, s[100:101]
	v_cmp_eq_u32_e64 s[100:101], 13, v2
	v_cndmask_b32_e64 v8, v8, v34, s[98:99]
	v_cmp_eq_u32_e64 s[98:99], 14, v2
	v_cndmask_b32_e32 v8, v8, v33, vcc
	v_cmp_eq_u32_e32 vcc, 15, v2
	v_cndmask_b32_e64 v8, v8, v32, s[100:101]
	v_cndmask_b32_e64 v8, v8, v11, s[98:99]
	v_cndmask_b32_e32 v2, v8, v6, vcc
	v_lshl_add_u32 v2, v7, 7, v2
	v_bfe_u32 v7, v81, 4, 4
	v_and_or_b32 v238, v7, 7, v241
	v_bfe_i32 v239, v7, 3, 1
	v_perm_b32 v240, v235, v234, v238
	v_perm_b32 v238, v237, v236, v238
	v_bfi_b32 v7, v239, v238, v240
	v_and_b32_e32 v8, 15, v81
	v_and_or_b32 v238, v8, 7, v241
	v_bfe_i32 v239, v8, 3, 1
	v_perm_b32 v240, v231, v230, v238
	v_perm_b32 v238, v233, v232, v238
	v_bfi_b32 v8, v239, v238, v240
	v_lshl_add_u32 v9, v7, 7, v8
	v_bfe_u32 v7, v79, 4, 4
	v_and_or_b32 v238, v7, 7, v241
	v_bfe_i32 v239, v7, 3, 1
	v_perm_b32 v240, v235, v234, v238
	v_perm_b32 v238, v237, v236, v238
	v_bfi_b32 v7, v239, v238, v240
	v_and_b32_e32 v8, 15, v79
	v_and_or_b32 v238, v8, 7, v241
	v_bfe_i32 v239, v8, 3, 1
	v_perm_b32 v240, v231, v230, v238
	v_perm_b32 v238, v233, v232, v238
	v_bfi_b32 v8, v239, v238, v240
	v_lshl_add_u32 v8, v7, 7, v8
	v_bfe_u32 v7, v77, 4, 4
	v_and_or_b32 v238, v7, 7, v241
	v_bfe_i32 v239, v7, 3, 1
	v_perm_b32 v240, v235, v234, v238
	v_perm_b32 v238, v237, v236, v238
	v_bfi_b32 v7, v239, v238, v240
	v_and_b32_e32 v17, 15, v77
	v_and_or_b32 v238, v17, 7, v241
	v_bfe_i32 v239, v17, 3, 1
	v_perm_b32 v240, v231, v230, v238
	v_perm_b32 v238, v233, v232, v238
	v_bfi_b32 v17, v239, v238, v240
	v_lshl_add_u32 v7, v7, 7, v17
	v_bfe_u32 v17, v75, 4, 4
	v_and_or_b32 v238, v17, 7, v241
	v_bfe_i32 v239, v17, 3, 1
	v_perm_b32 v240, v235, v234, v238
	v_perm_b32 v238, v237, v236, v238
	v_bfi_b32 v17, v239, v238, v240
	v_and_b32_e32 v18, 15, v75
	v_cmp_eq_u32_e32 vcc, 0, v18
	v_cmp_eq_u32_e64 s[100:101], 1, v18
	v_cmp_eq_u32_e64 s[98:99], 2, v18
	v_cndmask_b32_e32 v19, 0, v45, vcc
	v_cmp_eq_u32_e32 vcc, 3, v18
	v_cndmask_b32_e64 v19, v19, v44, s[100:101]
	v_cmp_eq_u32_e64 s[100:101], 4, v18
	v_cndmask_b32_e64 v19, v19, v43, s[98:99]
	v_cmp_eq_u32_e64 s[98:99], 5, v18
	v_cndmask_b32_e32 v19, v19, v42, vcc
	v_cmp_eq_u32_e32 vcc, 6, v18
	v_cndmask_b32_e64 v19, v19, v41, s[100:101]
	v_cmp_eq_u32_e64 s[100:101], 7, v18
	v_cndmask_b32_e64 v19, v19, v40, s[98:99]
	v_cmp_eq_u32_e64 s[98:99], 8, v18
	v_cndmask_b32_e32 v19, v19, v39, vcc
	v_cmp_eq_u32_e32 vcc, 9, v18
	v_cndmask_b32_e64 v19, v19, v38, s[100:101]
	v_cmp_eq_u32_e64 s[100:101], 10, v18
	v_cndmask_b32_e64 v19, v19, v37, s[98:99]
	v_cmp_eq_u32_e64 s[98:99], 11, v18
	v_cndmask_b32_e32 v19, v19, v36, vcc
	v_cmp_eq_u32_e32 vcc, 12, v18
	v_cndmask_b32_e64 v19, v19, v35, s[100:101]
	v_cmp_eq_u32_e64 s[100:101], 13, v18
	v_cndmask_b32_e64 v19, v19, v34, s[98:99]
	v_cmp_eq_u32_e64 s[98:99], 14, v18
	v_cndmask_b32_e32 v19, v19, v33, vcc
	v_cmp_eq_u32_e32 vcc, 15, v18
	v_cndmask_b32_e64 v19, v19, v32, s[100:101]
	v_cndmask_b32_e64 v11, v19, v11, s[98:99]
	v_cndmask_b32_e32 v6, v11, v6, vcc
	v_lshl_add_u32 v6, v17, 7, v6
	global_store_dwordx4 v[14:15], v[6:9], off offset:32
	global_store_dwordx4 v[14:15], v[2:5], off offset:48
	s_nop 1
	v_pk_mul_f32 v[4:5], v[26:27], v[10:11] op_sel_hi:[1,0]
	v_pk_mul_f32 v[2:3], v[24:25], v[10:11] op_sel_hi:[1,0]
	global_store_dwordx4 v[12:13], v[2:5], off offset:32
; __device__ __forceinline__ void phase_route(CArgs& A, int l, unsigned char* lds, int tid) {
;     ...
;         for (int k = 0; k < 16; ++k) { const unsigned ci = L3[k] & 0xFFu, i = ci >> 4, j = ci & 15u; unsigned e1 = 0u, e2 = 0u;
; #pragma unroll
;             for (int ii = 0; ii < 16; ++ii) { e1 = (i == (unsigned)ii) ? (L1[ii] & 0x7Fu) : e1; e2 = (j == (unsigned)ii) ? (L2[ii] & 0x7Fu) : e2; }
;             ex[k] = (int)(e1 * 128u + e2); e[k] *= inv; }
;         int* ip = IDX + (size_t)t * 128 + hd * 16; float* gp = GATE + (size_t)t * 128 + hd * 16;
;         if (hf == 0) {
;             *(int4*)ip = make_int4(ex[0], ex[1], ex[2], ex[3]); *(int4*)(ip + 4) = make_int4(ex[4], ex[5], ex[6], ex[7]);
;             *(f32x4*)gp = (f32x4){e[0], e[1], e[2], e[3]}; *(f32x4*)(gp + 4) = (f32x4){e[4], e[5], e[6], e[7]};
;         } else {
;             *(int4*)(ip + 8) = make_int4(ex[8], ex[9], ex[10], ex[11]); *(int4*)(ip + 12) = make_int4(ex[12], ex[13], ex[14], ex[15]);
;             *(f32x4*)(gp + 8) = (f32x4){e[8], e[9], e[10], e[11]}; *(f32x4*)(gp + 12) = (f32x4){e[12], e[13], e[14], e[15]};
.LBB0_137:
	s_or_saveexec_b64 s[4:5], s[4:5]
	s_nop 0
	v_mov_b64_e32 v[2:3], 48
	s_xor_b64 exec, exec, s[4:5]
	s_cbranch_execz .LBB0_130
	v_bfe_u32 v2, v84, 4, 4
	v_mov_b32_e32 v241, 0x0c0c0c00
	v_lshl_or_b32 v230, v71, 8, v72
	v_lshl_or_b32 v230, v70, 16, v230
	v_lshl_or_b32 v230, v69, 24, v230
	v_lshl_or_b32 v231, v67, 8, v68
	v_lshl_or_b32 v231, v61, 16, v231
	v_lshl_or_b32 v231, v60, 24, v231
	v_lshl_or_b32 v232, v52, 8, v53
	v_lshl_or_b32 v232, v51, 16, v232
	v_lshl_or_b32 v232, v50, 24, v232
	v_lshl_or_b32 v233, v48, 8, v49
	v_lshl_or_b32 v233, v47, 16, v233
	v_lshl_or_b32 v233, v46, 24, v233
	v_and_or_b32 v238, v2, 7, v241
	v_bfe_i32 v239, v2, 3, 1
	v_perm_b32 v240, v231, v230, v238
	v_perm_b32 v238, v233, v232, v238
	v_bfi_b32 v2, v239, v238, v240
	v_and_b32_e32 v3, 15, v84
	v_lshl_or_b32 v234, v44, 8, v45
	v_lshl_or_b32 v234, v43, 16, v234
	v_lshl_or_b32 v234, v42, 24, v234
	v_lshl_or_b32 v235, v40, 8, v41
	v_lshl_or_b32 v235, v39, 16, v235
	v_lshl_or_b32 v235, v38, 24, v235
	v_lshl_or_b32 v236, v36, 8, v37
	v_lshl_or_b32 v236, v35, 16, v236
	v_lshl_or_b32 v236, v34, 24, v236
	v_lshl_or_b32 v237, v32, 8, v33
	v_lshl_or_b32 v237, v11, 16, v237
	v_lshl_or_b32 v237, v6, 24, v237
	v_and_or_b32 v238, v3, 7, v241
	v_bfe_i32 v239, v3, 3, 1
	v_perm_b32 v240, v235, v234, v238
	v_perm_b32 v238, v237, v236, v238
	v_bfi_b32 v3, v239, v238, v240
	v_lshl_add_u32 v5, v2, 7, v3
	v_bfe_u32 v2, v83, 4, 4
	v_and_or_b32 v238, v2, 7, v241
	v_bfe_i32 v239, v2, 3, 1
	v_perm_b32 v240, v231, v230, v238
	v_perm_b32 v238, v233, v232, v238
	v_bfi_b32 v2, v239, v238, v240
	v_and_b32_e32 v3, 15, v83
	v_and_or_b32 v238, v3, 7, v241
	v_bfe_i32 v239, v3, 3, 1
	v_perm_b32 v240, v235, v234, v238
	v_perm_b32 v238, v237, v236, v238
	v_bfi_b32 v3, v239, v238, v240
	v_lshl_add_u32 v4, v2, 7, v3
	v_bfe_u32 v2, v82, 4, 4
	v_and_or_b32 v238, v2, 7, v241
	v_bfe_i32 v239, v2, 3, 1
	v_perm_b32 v240, v231, v230, v238
	v_perm_b32 v238, v233, v232, v238
	v_bfi_b32 v2, v239, v238, v240
	v_and_b32_e32 v3, 15, v82
	v_and_or_b32 v238, v3, 7, v241
	v_bfe_i32 v239, v3, 3, 1
	v_perm_b32 v240, v235, v234, v238
	v_perm_b32 v238, v237, v236, v238
	v_bfi_b32 v3, v239, v238, v240
	v_lshl_add_u32 v3, v2, 7, v3
	v_bfe_u32 v2, v80, 4, 4
	v_and_or_b32 v238, v2, 7, v241
	v_bfe_i32 v239, v2, 3, 1
	v_perm_b32 v240, v231, v230, v238
	v_perm_b32 v238, v233, v232, v238
	v_bfi_b32 v2, v239, v238, v240
	v_and_b32_e32 v7, 15, v80
	v_and_or_b32 v238, v7, 7, v241
	v_bfe_i32 v239, v7, 3, 1
	v_perm_b32 v240, v235, v234, v238
	v_perm_b32 v238, v237, v236, v238
	v_bfi_b32 v7, v239, v238, v240
	v_lshl_add_u32 v2, v2, 7, v7
	v_bfe_u32 v7, v78, 4, 4
	v_and_or_b32 v238, v7, 7, v241
	v_bfe_i32 v239, v7, 3, 1
	v_perm_b32 v240, v231, v230, v238
	v_perm_b32 v238, v233, v232, v238
	v_bfi_b32 v7, v239, v238, v240
	v_and_b32_e32 v8, 15, v78
	v_and_or_b32 v238, v8, 7, v241
	v_bfe_i32 v239, v8, 3, 1
	v_perm_b32 v240, v235, v234, v238
	v_perm_b32 v238, v237, v236, v238
	v_bfi_b32 v8, v239, v238, v240
	v_lshl_add_u32 v9, v7, 7, v8
	v_bfe_u32 v7, v76, 4, 4
	v_and_or_b32 v238, v7, 7, v241
	v_bfe_i32 v239, v7, 3, 1
	v_perm_b32 v240, v231, v230, v238
	v_perm_b32 v238, v233, v232, v238
	v_bfi_b32 v7, v239, v238, v240
	v_and_b32_e32 v8, 15, v76
	v_and_or_b32 v238, v8, 7, v241
	v_bfe_i32 v239, v8, 3, 1
	v_perm_b32 v240, v235, v234, v238
	v_perm_b32 v238, v237, v236, v238
	v_bfi_b32 v8, v239, v238, v240
	v_lshl_add_u32 v8, v7, 7, v8
	v_bfe_u32 v7, v74, 4, 4
	v_and_or_b32 v238, v7, 7, v241
	v_bfe_i32 v239, v7, 3, 1
	v_perm_b32 v240, v231, v230, v238
	v_perm_b32 v238, v233, v232, v238
	v_bfi_b32 v7, v239, v238, v240
	v_and_b32_e32 v24, 15, v74
	v_and_or_b32 v238, v24, 7, v241
	v_bfe_i32 v239, v24, 3, 1
	v_perm_b32 v240, v235, v234, v238
	v_perm_b32 v238, v237, v236, v238
	v_bfi_b32 v24, v239, v238, v240
	v_lshl_add_u32 v7, v7, 7, v24
	v_bfe_u32 v24, v73, 4, 4
	v_and_or_b32 v238, v24, 7, v241
	v_bfe_i32 v239, v24, 3, 1
	v_perm_b32 v240, v231, v230, v238
	v_perm_b32 v238, v233, v232, v238
	v_bfi_b32 v24, v239, v238, v240
	v_and_b32_e32 v25, 15, v73
	v_cmp_eq_u32_e32 vcc, 0, v25
	v_cmp_eq_u32_e64 s[100:101], 1, v25
	v_cmp_eq_u32_e64 s[98:99], 2, v25
	v_cndmask_b32_e32 v26, 0, v45, vcc
	v_cmp_eq_u32_e32 vcc, 3, v25
	v_cndmask_b32_e64 v26, v26, v44, s[100:101]
	v_cmp_eq_u32_e64 s[100:101], 4, v25
	v_cndmask_b32_e64 v26, v26, v43, s[98:99]
	v_cmp_eq_u32_e64 s[98:99], 5, v25
	v_cndmask_b32_e32 v26, v26, v42, vcc
	v_cmp_eq_u32_e32 vcc, 6, v25
	v_cndmask_b32_e64 v26, v26, v41, s[100:101]
	v_cmp_eq_u32_e64 s[100:101], 7, v25
	v_cndmask_b32_e64 v26, v26, v40, s[98:99]
	v_cmp_eq_u32_e64 s[98:99], 8, v25
	v_cndmask_b32_e32 v26, v26, v39, vcc
	v_cmp_eq_u32_e32 vcc, 9, v25
	v_cndmask_b32_e64 v26, v26, v38, s[100:101]
	v_cmp_eq_u32_e64 s[100:101], 10, v25
	v_cndmask_b32_e64 v26, v26, v37, s[98:99]
	v_cmp_eq_u32_e64 s[98:99], 11, v25
	v_cndmask_b32_e32 v26, v26, v36, vcc
	v_cmp_eq_u32_e32 vcc, 12, v25
	v_cndmask_b32_e64 v26, v26, v35, s[100:101]
	v_cmp_eq_u32_e64 s[100:101], 13, v25
	v_cndmask_b32_e64 v26, v26, v34, s[98:99]
	v_cmp_eq_u32_e64 s[98:99], 14, v25
	v_cndmask_b32_e32 v26, v26, v33, vcc
	v_cmp_eq_u32_e32 vcc, 15, v25
	v_cndmask_b32_e64 v26, v26, v32, s[100:101]
	v_cndmask_b32_e64 v11, v26, v11, s[98:99]
	v_cndmask_b32_e32 v6, v11, v6, vcc
	v_lshl_add_u32 v6, v24, 7, v6
	global_store_dwordx4 v[14:15], v[6:9], off
	global_store_dwordx4 v[14:15], v[2:5], off offset:16
	s_nop 1
	v_pk_mul_f32 v[4:5], v[18:19], v[10:11] op_sel_hi:[1,0]
	v_pk_mul_f32 v[2:3], v[16:17], v[10:11] op_sel_hi:[1,0]
	global_store_dwordx4 v[12:13], v[2:5], off
	s_nop 1
	v_mov_b64_e32 v[2:3], 16
	s_branch .LBB0_130
